# combo1 + attention K/V prefetch two tiles ahead + P.V fragment double-buffering + GEMM epilogue stagger (gate/up, w_in)
# baseline (speedup 1.0000x reference)
; __device__ __forceinline__ unsigned cvt_pk_bf16(float lo, float hi) { unsigned r; asm volatile("v_cvt_pk_bf16_f32 %0, %1, %2" : "=v"(r) : "v"(lo), "v"(hi)); return r; }
; #define PG8_BAR __builtin_amdgcn_s_barrier()
; template <class Epi>
; __device__ __forceinline__ void gemm_phase(LAS unsigned char* lds, const Gemm g, const StaticOrder& S, const Epi& E, const int tid) {
;     ...
;         if (wr == 0) PG8_BAR;
;     __device__ __forceinline__ void operator()(f32x4 (&acc)[2][2][4][2], const Unit& u, int wr, int wc, int fr, int fq) const {
;         const int row0 = u.pm * BM + wr * 64 + fr, col0 = u.pn * 128 + wc * 32 + 8 * fq;
; #pragma unroll
;         for (int ai = 0; ai < 2; ++ai)
; #pragma unroll
;             for (int m = 0; m < 4; ++m) {
;                 bf16* rowp = O + (size_t)(row0 + ai * HALF + m * 16) * FF + col0;
;                 const f32x4 g0 = acc[ai][0][m][0], g1 = acc[ai][0][m][1], u0 = acc[ai][1][m][0], u1 = acc[ai][1][m][1];
;                 u32x4 w;
;                 const f32x4 a0 = swiglu4(g0, u0), a1 = swiglu4(g1, u1);
;                 w.x = cvt_pk_bf16(a0[0], a0[1]); w.y = cvt_pk_bf16(a0[2], a0[3]); w.z = cvt_pk_bf16(a1[0], a1[1]); w.w = cvt_pk_bf16(a1[2], a1[3]);
;                 __builtin_nontemporal_store(w, (u32x4*)rowp);
;             }
.LBB0_164:
	v_pk_mul_f32 v[150:151], v[126:127], s[74:75] op_sel_hi:[1,0]
	v_pk_mul_f32 v[152:153], v[124:125], s[74:75] op_sel_hi:[1,0]
	v_pk_mul_f32 v[122:123], v[126:127], v[122:123]
	v_pk_mul_f32 v[120:121], v[124:125], v[120:121]
	v_pk_mul_f32 v[124:125], v[118:119], s[74:75] op_sel_hi:[1,0]
	v_pk_mul_f32 v[126:127], v[116:117], s[74:75] op_sel_hi:[1,0]
	v_exp_f32_e32 v124, v124
	v_exp_f32_e32 v126, v126
	v_exp_f32_e32 v125, v125
	v_exp_f32_e32 v127, v127
	v_exp_f32_e32 v152, v152
	v_exp_f32_e32 v150, v150
	v_exp_f32_e32 v151, v151
	v_exp_f32_e32 v153, v153
	v_pk_add_f32 v[124:125], v[124:125], 1.0 op_sel_hi:[1,0]
	v_pk_add_f32 v[126:127], v[126:127], 1.0 op_sel_hi:[1,0]
	v_pk_add_f32 v[150:151], v[150:151], 1.0 op_sel_hi:[1,0]
	v_pk_add_f32 v[152:153], v[152:153], 1.0 op_sel_hi:[1,0]
	v_rcp_f32_e32 v126, v126
	v_rcp_f32_e32 v124, v124
	v_rcp_f32_e32 v125, v125
	v_rcp_f32_e32 v127, v127
	v_readlane_b32 s0, v254, 23
	v_rcp_f32_e32 v152, v152
	v_rcp_f32_e32 v153, v153
	v_rcp_f32_e32 v150, v150
	v_rcp_f32_e32 v151, v151
	v_lshl_or_b32 v140, s49, 7, v144
	v_readlane_b32 s1, v254, 24
	v_lshl_add_u32 v146, s52, 8, v142
	v_ashrrev_i32_e32 v141, 31, v140
	v_mov_b64_e32 v[138:139], s[0:1]
	s_movk_i32 s2, 0x2c00
	v_pk_mul_f32 v[114:115], v[118:119], v[114:115]
	v_pk_mul_f32 v[112:113], v[116:117], v[112:113]
	v_mad_i64_i32 v[148:149], s[0:1], v146, s2, v[138:139]
	v_lshlrev_b64 v[140:141], 1, v[140:141]
	v_pk_mul_f32 v[116:117], v[124:125], v[114:115]
	v_pk_mul_f32 v[114:115], v[126:127], v[112:113]
	v_lshl_add_u64 v[148:149], v[148:149], 0, v[140:141]
	v_pk_mul_f32 v[122:123], v[150:151], v[122:123]
	v_pk_mul_f32 v[120:121], v[152:153], v[120:121]
	v_pk_mul_f32 v[106:107], v[110:111], v[106:107]
	v_cvt_pk_bf16_f32 v112, v120, v121
	v_cvt_pk_bf16_f32 v113, v122, v123
	v_cvt_pk_bf16_f32 v114, v114, v115
	v_cvt_pk_bf16_f32 v115, v116, v117
	global_store_dwordx4 v[148:149], v[112:115], off nt
	v_pk_mul_f32 v[104:105], v[108:109], v[104:105]
	v_or_b32_e32 v116, 16, v146
	v_pk_mul_f32 v[112:113], v[110:111], s[74:75] op_sel_hi:[1,0]
	v_pk_mul_f32 v[114:115], v[108:109], s[74:75] op_sel_hi:[1,0]
	v_pk_mul_f32 v[108:109], v[102:103], s[74:75] op_sel_hi:[1,0]
	v_pk_mul_f32 v[110:111], v[100:101], s[74:75] op_sel_hi:[1,0]
	v_exp_f32_e32 v108, v108
	v_exp_f32_e32 v110, v110
	v_exp_f32_e32 v109, v109
	v_exp_f32_e32 v111, v111
	v_exp_f32_e32 v114, v114
	v_exp_f32_e32 v115, v115
	v_exp_f32_e32 v112, v112
	v_exp_f32_e32 v113, v113
	v_pk_add_f32 v[108:109], v[108:109], 1.0 op_sel_hi:[1,0]
	v_pk_add_f32 v[110:111], v[110:111], 1.0 op_sel_hi:[1,0]
	v_pk_add_f32 v[114:115], v[114:115], 1.0 op_sel_hi:[1,0]
	v_pk_add_f32 v[112:113], v[112:113], 1.0 op_sel_hi:[1,0]
	v_rcp_f32_e32 v110, v110
	v_rcp_f32_e32 v108, v108
	v_rcp_f32_e32 v109, v109
	v_rcp_f32_e32 v111, v111
	v_rcp_f32_e32 v114, v114
	v_rcp_f32_e32 v115, v115
	v_rcp_f32_e32 v112, v112
	v_rcp_f32_e32 v113, v113
	v_pk_mul_f32 v[98:99], v[102:103], v[98:99]
	v_pk_mul_f32 v[96:97], v[100:101], v[96:97]
	v_mad_i64_i32 v[116:117], s[0:1], v116, s2, v[138:139]
	v_pk_mul_f32 v[100:101], v[108:109], v[98:99]
	v_pk_mul_f32 v[98:99], v[110:111], v[96:97]
	v_lshl_add_u64 v[116:117], v[116:117], 0, v[140:141]
	v_pk_mul_f32 v[106:107], v[112:113], v[106:107]
	v_pk_mul_f32 v[104:105], v[114:115], v[104:105]
	v_pk_mul_f32 v[90:91], v[94:95], v[90:91]
	v_cvt_pk_bf16_f32 v96, v104, v105
	v_cvt_pk_bf16_f32 v97, v106, v107
	v_cvt_pk_bf16_f32 v98, v98, v99
	v_cvt_pk_bf16_f32 v99, v100, v101
	global_store_dwordx4 v[116:117], v[96:99], off nt
	v_pk_mul_f32 v[88:89], v[92:93], v[88:89]
	v_or_b32_e32 v100, 32, v146
	v_pk_mul_f32 v[96:97], v[94:95], s[74:75] op_sel_hi:[1,0]
	v_pk_mul_f32 v[98:99], v[92:93], s[74:75] op_sel_hi:[1,0]
	v_pk_mul_f32 v[92:93], v[86:87], s[74:75] op_sel_hi:[1,0]
	v_pk_mul_f32 v[94:95], v[84:85], s[74:75] op_sel_hi:[1,0]
	v_exp_f32_e32 v92, v92
	v_exp_f32_e32 v94, v94
	v_exp_f32_e32 v93, v93
	v_exp_f32_e32 v95, v95
	v_exp_f32_e32 v98, v98
	v_exp_f32_e32 v99, v99
	v_exp_f32_e32 v96, v96
	v_exp_f32_e32 v97, v97
	v_pk_add_f32 v[92:93], v[92:93], 1.0 op_sel_hi:[1,0]
	v_pk_add_f32 v[94:95], v[94:95], 1.0 op_sel_hi:[1,0]
	v_pk_add_f32 v[98:99], v[98:99], 1.0 op_sel_hi:[1,0]
	v_pk_add_f32 v[96:97], v[96:97], 1.0 op_sel_hi:[1,0]
	v_rcp_f32_e32 v94, v94
	v_rcp_f32_e32 v92, v92
	v_rcp_f32_e32 v93, v93
	v_rcp_f32_e32 v95, v95
	v_rcp_f32_e32 v98, v98
	v_rcp_f32_e32 v99, v99
	v_rcp_f32_e32 v96, v96
	v_rcp_f32_e32 v97, v97
	v_pk_mul_f32 v[82:83], v[86:87], v[82:83]
	v_pk_mul_f32 v[80:81], v[84:85], v[80:81]
	v_mad_i64_i32 v[100:101], s[0:1], v100, s2, v[138:139]
	v_pk_mul_f32 v[84:85], v[92:93], v[82:83]
	v_pk_mul_f32 v[82:83], v[94:95], v[80:81]
	v_lshl_add_u64 v[100:101], v[100:101], 0, v[140:141]
	v_pk_mul_f32 v[90:91], v[96:97], v[90:91]
	v_pk_mul_f32 v[88:89], v[98:99], v[88:89]
	v_pk_mul_f32 v[74:75], v[78:79], v[74:75]
	v_cvt_pk_bf16_f32 v80, v88, v89
	v_cvt_pk_bf16_f32 v81, v90, v91
	v_cvt_pk_bf16_f32 v82, v82, v83
	v_cvt_pk_bf16_f32 v83, v84, v85
	global_store_dwordx4 v[100:101], v[80:83], off nt
	v_pk_mul_f32 v[72:73], v[76:77], v[72:73]
	v_or_b32_e32 v84, 48, v146
	v_pk_mul_f32 v[80:81], v[78:79], s[74:75] op_sel_hi:[1,0]
	v_pk_mul_f32 v[82:83], v[76:77], s[74:75] op_sel_hi:[1,0]
	v_pk_mul_f32 v[76:77], v[70:71], s[74:75] op_sel_hi:[1,0]
	v_pk_mul_f32 v[78:79], v[68:69], s[74:75] op_sel_hi:[1,0]
	v_exp_f32_e32 v76, v76
	v_exp_f32_e32 v78, v78
	v_exp_f32_e32 v77, v77
	v_exp_f32_e32 v79, v79
	v_exp_f32_e32 v82, v82
	v_exp_f32_e32 v83, v83
	v_exp_f32_e32 v80, v80
	v_exp_f32_e32 v81, v81
	v_pk_add_f32 v[76:77], v[76:77], 1.0 op_sel_hi:[1,0]
	v_pk_add_f32 v[78:79], v[78:79], 1.0 op_sel_hi:[1,0]
; __device__ __forceinline__ unsigned cvt_pk_bf16(float lo, float hi) { unsigned r; asm volatile("v_cvt_pk_bf16_f32 %0, %1, %2" : "=v"(r) : "v"(lo), "v"(hi)); return r; }
; #define PG8_BAR __builtin_amdgcn_s_barrier()
; template <class Epi>
; __device__ __forceinline__ void gemm_phase(LAS unsigned char* lds, const Gemm g, const StaticOrder& S, const Epi& E, const int tid) {
;     ...
;         if (wr == 0) PG8_BAR;
;     __device__ __forceinline__ void operator()(f32x4 (&acc)[2][2][4][2], const Unit& u, int wr, int wc, int fr, int fq) const {
;     ...
;             for (int m = 0; m < 4; ++m) {
;                 bf16* rowp = O + (size_t)(row0 + ai * HALF + m * 16) * FF + col0;
;                 const f32x4 g0 = acc[ai][0][m][0], g1 = acc[ai][0][m][1], u0 = acc[ai][1][m][0], u1 = acc[ai][1][m][1];
;                 u32x4 w;
;                 const f32x4 a0 = swiglu4(g0, u0), a1 = swiglu4(g1, u1);
;                 w.x = cvt_pk_bf16(a0[0], a0[1]); w.y = cvt_pk_bf16(a0[2], a0[3]); w.z = cvt_pk_bf16(a1[0], a1[1]); w.w = cvt_pk_bf16(a1[2], a1[3]);
;                 __builtin_nontemporal_store(w, (u32x4*)rowp);
;             }
	v_pk_add_f32 v[82:83], v[82:83], 1.0 op_sel_hi:[1,0]
	v_pk_add_f32 v[80:81], v[80:81], 1.0 op_sel_hi:[1,0]
	v_rcp_f32_e32 v78, v78
	v_rcp_f32_e32 v76, v76
	v_rcp_f32_e32 v77, v77
	v_rcp_f32_e32 v79, v79
	v_rcp_f32_e32 v82, v82
	v_rcp_f32_e32 v83, v83
	v_rcp_f32_e32 v80, v80
	v_rcp_f32_e32 v81, v81
	v_pk_mul_f32 v[66:67], v[70:71], v[66:67]
	v_pk_mul_f32 v[64:65], v[68:69], v[64:65]
	v_mad_i64_i32 v[84:85], s[0:1], v84, s2, v[138:139]
	v_pk_mul_f32 v[68:69], v[76:77], v[66:67]
	v_pk_mul_f32 v[66:67], v[78:79], v[64:65]
	v_lshl_add_u64 v[84:85], v[84:85], 0, v[140:141]
	v_pk_mul_f32 v[74:75], v[80:81], v[74:75]
	v_pk_mul_f32 v[72:73], v[82:83], v[72:73]
	v_pk_mul_f32 v[58:59], v[62:63], v[58:59]
	v_cvt_pk_bf16_f32 v64, v72, v73
	v_cvt_pk_bf16_f32 v65, v74, v75
	v_cvt_pk_bf16_f32 v66, v66, v67
	v_cvt_pk_bf16_f32 v67, v68, v69
	global_store_dwordx4 v[84:85], v[64:67], off nt
	v_pk_mul_f32 v[56:57], v[60:61], v[56:57]
	v_add_u32_e32 v68, 0x80, v146
	v_pk_mul_f32 v[64:65], v[62:63], s[74:75] op_sel_hi:[1,0]
	v_pk_mul_f32 v[66:67], v[60:61], s[74:75] op_sel_hi:[1,0]
	v_pk_mul_f32 v[60:61], v[54:55], s[74:75] op_sel_hi:[1,0]
	v_pk_mul_f32 v[62:63], v[52:53], s[74:75] op_sel_hi:[1,0]
	v_exp_f32_e32 v60, v60
	v_exp_f32_e32 v62, v62
	v_exp_f32_e32 v61, v61
	v_exp_f32_e32 v63, v63
	v_exp_f32_e32 v66, v66
	v_exp_f32_e32 v67, v67
	v_exp_f32_e32 v64, v64
	v_exp_f32_e32 v65, v65
	v_pk_add_f32 v[60:61], v[60:61], 1.0 op_sel_hi:[1,0]
	v_pk_add_f32 v[62:63], v[62:63], 1.0 op_sel_hi:[1,0]
	v_pk_add_f32 v[66:67], v[66:67], 1.0 op_sel_hi:[1,0]
	v_pk_add_f32 v[64:65], v[64:65], 1.0 op_sel_hi:[1,0]
	v_rcp_f32_e32 v62, v62
	v_rcp_f32_e32 v60, v60
	v_rcp_f32_e32 v61, v61
	v_rcp_f32_e32 v63, v63
	v_rcp_f32_e32 v66, v66
	v_rcp_f32_e32 v67, v67
	v_rcp_f32_e32 v64, v64
	v_rcp_f32_e32 v65, v65
	v_pk_mul_f32 v[50:51], v[54:55], v[50:51]
	v_pk_mul_f32 v[48:49], v[52:53], v[48:49]
	v_mad_i64_i32 v[68:69], s[0:1], v68, s2, v[138:139]
	v_pk_mul_f32 v[52:53], v[60:61], v[50:51]
	v_pk_mul_f32 v[50:51], v[62:63], v[48:49]
	v_lshl_add_u64 v[68:69], v[68:69], 0, v[140:141]
	v_pk_mul_f32 v[58:59], v[64:65], v[58:59]
	v_pk_mul_f32 v[56:57], v[66:67], v[56:57]
	v_pk_mul_f32 v[42:43], v[46:47], v[42:43]
	v_cvt_pk_bf16_f32 v48, v56, v57
	v_cvt_pk_bf16_f32 v49, v58, v59
	v_cvt_pk_bf16_f32 v50, v50, v51
	v_cvt_pk_bf16_f32 v51, v52, v53
	global_store_dwordx4 v[68:69], v[48:51], off nt
	v_pk_mul_f32 v[40:41], v[44:45], v[40:41]
	v_add_u32_e32 v52, 0x90, v146
	v_pk_mul_f32 v[48:49], v[46:47], s[74:75] op_sel_hi:[1,0]
	v_pk_mul_f32 v[50:51], v[44:45], s[74:75] op_sel_hi:[1,0]
	v_pk_mul_f32 v[44:45], v[38:39], s[74:75] op_sel_hi:[1,0]
	v_pk_mul_f32 v[46:47], v[36:37], s[74:75] op_sel_hi:[1,0]
	v_exp_f32_e32 v44, v44
	v_exp_f32_e32 v46, v46
	v_exp_f32_e32 v45, v45
	v_exp_f32_e32 v47, v47
	v_exp_f32_e32 v50, v50
	v_exp_f32_e32 v51, v51
	v_exp_f32_e32 v48, v48
	v_exp_f32_e32 v49, v49
	v_pk_add_f32 v[44:45], v[44:45], 1.0 op_sel_hi:[1,0]
	v_pk_add_f32 v[46:47], v[46:47], 1.0 op_sel_hi:[1,0]
	v_pk_add_f32 v[50:51], v[50:51], 1.0 op_sel_hi:[1,0]
	v_pk_add_f32 v[48:49], v[48:49], 1.0 op_sel_hi:[1,0]
	v_rcp_f32_e32 v46, v46
	v_rcp_f32_e32 v44, v44
	v_rcp_f32_e32 v45, v45
	v_rcp_f32_e32 v47, v47
	v_rcp_f32_e32 v50, v50
	v_rcp_f32_e32 v51, v51
	v_rcp_f32_e32 v48, v48
	v_rcp_f32_e32 v49, v49
	v_pk_mul_f32 v[34:35], v[38:39], v[34:35]
	v_pk_mul_f32 v[32:33], v[36:37], v[32:33]
	v_mad_i64_i32 v[52:53], s[0:1], v52, s2, v[138:139]
	v_pk_mul_f32 v[36:37], v[44:45], v[34:35]
	v_pk_mul_f32 v[34:35], v[46:47], v[32:33]
	v_lshl_add_u64 v[52:53], v[52:53], 0, v[140:141]
	v_pk_mul_f32 v[42:43], v[48:49], v[42:43]
	v_pk_mul_f32 v[40:41], v[50:51], v[40:41]
	v_pk_mul_f32 v[26:27], v[30:31], v[26:27]
	v_cvt_pk_bf16_f32 v32, v40, v41
	v_cvt_pk_bf16_f32 v33, v42, v43
	v_cvt_pk_bf16_f32 v34, v34, v35
	v_cvt_pk_bf16_f32 v35, v36, v37
	global_store_dwordx4 v[52:53], v[32:35], off nt
	v_pk_mul_f32 v[24:25], v[28:29], v[24:25]
	v_add_u32_e32 v36, 0xa0, v146
	v_pk_mul_f32 v[32:33], v[30:31], s[74:75] op_sel_hi:[1,0]
	v_pk_mul_f32 v[34:35], v[28:29], s[74:75] op_sel_hi:[1,0]
	v_pk_mul_f32 v[28:29], v[22:23], s[74:75] op_sel_hi:[1,0]
	v_pk_mul_f32 v[30:31], v[20:21], s[74:75] op_sel_hi:[1,0]
	v_exp_f32_e32 v28, v28
	v_exp_f32_e32 v30, v30
	v_exp_f32_e32 v29, v29
	v_exp_f32_e32 v31, v31
	v_exp_f32_e32 v34, v34
	v_exp_f32_e32 v35, v35
	v_exp_f32_e32 v32, v32
	v_exp_f32_e32 v33, v33
	v_pk_add_f32 v[28:29], v[28:29], 1.0 op_sel_hi:[1,0]
	v_pk_add_f32 v[30:31], v[30:31], 1.0 op_sel_hi:[1,0]
	v_pk_add_f32 v[34:35], v[34:35], 1.0 op_sel_hi:[1,0]
	v_pk_add_f32 v[32:33], v[32:33], 1.0 op_sel_hi:[1,0]
	v_rcp_f32_e32 v30, v30
	v_rcp_f32_e32 v28, v28
	v_rcp_f32_e32 v29, v29
	v_rcp_f32_e32 v31, v31
	v_rcp_f32_e32 v34, v34
	v_rcp_f32_e32 v35, v35
	v_rcp_f32_e32 v32, v32
	v_rcp_f32_e32 v33, v33
	v_pk_mul_f32 v[18:19], v[22:23], v[18:19]
	v_pk_mul_f32 v[16:17], v[20:21], v[16:17]
	v_mad_i64_i32 v[36:37], s[0:1], v36, s2, v[138:139]
	v_pk_mul_f32 v[20:21], v[28:29], v[18:19]
	v_pk_mul_f32 v[18:19], v[30:31], v[16:17]
	v_lshl_add_u64 v[36:37], v[36:37], 0, v[140:141]
	v_pk_mul_f32 v[26:27], v[32:33], v[26:27]
	v_pk_mul_f32 v[24:25], v[34:35], v[24:25]
	v_pk_mul_f32 v[10:11], v[14:15], v[10:11]
	v_cvt_pk_bf16_f32 v16, v24, v25
	v_cvt_pk_bf16_f32 v17, v26, v27
	v_cvt_pk_bf16_f32 v18, v18, v19
	v_cvt_pk_bf16_f32 v19, v20, v21
	global_store_dwordx4 v[36:37], v[16:19], off nt
	v_pk_mul_f32 v[8:9], v[12:13], v[8:9]
	v_add_u32_e32 v20, 0xb0, v146
	v_pk_mul_f32 v[16:17], v[14:15], s[74:75] op_sel_hi:[1,0]
	v_pk_mul_f32 v[18:19], v[12:13], s[74:75] op_sel_hi:[1,0]
	v_pk_mul_f32 v[12:13], v[6:7], s[74:75] op_sel_hi:[1,0]
	v_pk_mul_f32 v[14:15], v[4:5], s[74:75] op_sel_hi:[1,0]
	v_exp_f32_e32 v12, v12
	v_exp_f32_e32 v14, v14
	v_exp_f32_e32 v13, v13
	v_exp_f32_e32 v15, v15
	v_exp_f32_e32 v18, v18
	v_exp_f32_e32 v19, v19
	v_exp_f32_e32 v16, v16
	v_exp_f32_e32 v17, v17
	v_pk_add_f32 v[12:13], v[12:13], 1.0 op_sel_hi:[1,0]
	v_pk_add_f32 v[14:15], v[14:15], 1.0 op_sel_hi:[1,0]
	v_pk_add_f32 v[18:19], v[18:19], 1.0 op_sel_hi:[1,0]
	v_pk_add_f32 v[16:17], v[16:17], 1.0 op_sel_hi:[1,0]
	v_rcp_f32_e32 v14, v14
	v_rcp_f32_e32 v12, v12
	v_rcp_f32_e32 v13, v13
	v_rcp_f32_e32 v15, v15
	v_rcp_f32_e32 v18, v18
	v_rcp_f32_e32 v19, v19
	v_rcp_f32_e32 v16, v16
	v_rcp_f32_e32 v17, v17
	v_mad_i64_i32 v[20:21], s[0:1], v20, s2, v[138:139]
	v_pk_mul_f32 v[2:3], v[6:7], v[2:3]
	v_pk_mul_f32 v[0:1], v[4:5], v[0:1]
	v_lshl_add_u64 v[20:21], v[20:21], 0, v[140:141]
	v_pk_mul_f32 v[4:5], v[12:13], v[2:3]
	v_pk_mul_f32 v[2:3], v[14:15], v[0:1]
	s_andn2_b64 vcc, exec, s[36:37]
	s_mov_b64 s[0:1], -1
	v_readlane_b32 s58, v254, 62
	v_readlane_b32 s59, v254, 63
	v_pk_mul_f32 v[10:11], v[16:17], v[10:11]
	v_pk_mul_f32 v[8:9], v[18:19], v[8:9]
	s_nop 0
	v_cvt_pk_bf16_f32 v0, v8, v9
	v_cvt_pk_bf16_f32 v1, v10, v11
	v_cvt_pk_bf16_f32 v2, v2, v3
	v_cvt_pk_bf16_f32 v3, v4, v5
	global_store_dwordx4 v[20:21], v[0:3], off nt
	s_cmp_eq_u64 s[10:11], 0
	s_cbranch_scc1 .Lepi_gu1_nb
	s_barrier
; #define PG8_BAR __builtin_amdgcn_s_barrier()
; template <class Epi>
; __device__ __forceinline__ void gemm_phase(LAS unsigned char* lds, const Gemm g, const StaticOrder& S, const Epi& E, const int tid) {
;     ...
;         if (!has_next) break;
;         if (!(Epi::CHAIN && cur.n + 1 < S.NS)) {
; #pragma unroll
;         for (int a = 0; a < 2; ++a)
; #pragma unroll
;             for (int b = 0; b < 2; ++b)
; #pragma unroll
;                 for (int m = 0; m < 4; ++m)
; #pragma unroll
;                     for (int n = 0; n < 2; ++n) acc[a][b][m][n] = (f32x4){0.f, 0.f, 0.f, 0.f};
;         }
;         cur = nxt; cA = nA; cB = nB; ++ui;
;         if (wr == 1) PG8_BAR;
.Lepi_gu1_nb:
	s_cbranch_vccnz .LBB0_157
	s_andn2_b64 vcc, exec, s[8:9]
	s_cbranch_vccnz .LBB0_156
	s_barrier
	s_branch .LBB0_156

; #define PG8_STAGE(bufoff, gbase, voff) do { _Pragma("unroll") for (int _i = 0; _i < 2; ++_i) \
;         __builtin_amdgcn_global_load_lds((const unsigned*)((const char*)(gbase) + (voff)[_i]), (LAS unsigned*)(lds + (bufoff) + ldsw + _i * 8192), 16, 0, 0); } while (0)
; #define PG8_LDA(dst, b, h) do { _Pragma("unroll") for (int m = 0; m < 4; ++m) _Pragma("unroll") for (int k = 0; k < 2; ++k) dst[m][k] = *(const LAS bf16x8*)(lds + PG8_SA(b, h) + aoff + m * 2048 + k * 1024); } while (0)
; #define PG8_LDB(dst, b, h) do { _Pragma("unroll") for (int n = 0; n < 2; ++n) _Pragma("unroll") for (int k = 0; k < 2; ++k) dst[n][k] = *(const LAS bf16x8*)(lds + PG8_SB(b, h) + boff + n * 2048 + k * 1024); } while (0)
; #define PG8_MMA(ai, bj, At, Bt) do { __builtin_amdgcn_s_setprio(1); _Pragma("unroll") for (int m = 0; m < 4; ++m) _Pragma("unroll") for (int n = 0; n < 2; ++n) _Pragma("unroll") for (int k = 0; k < 2; ++k) \
;         acc[ai][bj][m][n] = __builtin_amdgcn_mfma_f32_16x16x32_bf16(Bt[n][k], At[m][k], acc[ai][bj][m][n], 0, 0, 0); __builtin_amdgcn_s_setprio(0); } while (0)
; #define PG8_WAIT_V(n) asm volatile("s_waitcnt vmcnt(" #n ")" ::: "memory")
; #define PG8_WAIT_L(n) asm volatile("s_waitcnt lgkmcnt(" #n ")" ::: "memory")
; #define PG8_BAR __builtin_amdgcn_s_barrier()
; #define PG8_SCHED __builtin_amdgcn_sched_barrier(0)
; template <class Epi>
; __device__ __forceinline__ void gemm_phase(LAS unsigned char* lds, const Gemm g, const StaticOrder& S, const Epi& E, const int tid) {
;     ...
;             PG8_LDB(B0, 0, 0); PG8_LDB(B1, 0, 1); PG8_SCHED; PG8_LDA(At, 0, 0); PG8_STAGE(PG8_SA(1, 1), a1 + hsA, voffA);
;             PG8_WAIT_V(8); PG8_WAIT_L(0); PG8_BAR; PG8_MMA(0, 0, At, B0); PG8_MMA(0, 1, At, B1); PG8_BAR; PG8_SCHED;
;             PG8_LDA(At, 0, 1); PG8_STAGE(PG8_SB(0, 0), b2, voffB); PG8_STAGE(PG8_SB(0, 1), b2 + hsB, voffB); PG8_STAGE(PG8_SA(0, 0), a2, voffA);
;             PG8_WAIT_V(8); PG8_WAIT_L(0); PG8_BAR; PG8_MMA(1, 0, At, B0); PG8_MMA(1, 1, At, B1); PG8_BAR; PG8_SCHED;
.LBB0_354:
	s_add_u32 s0, s36, 0xfff80080
	s_addc_u32 s1, s37, -1
	s_add_i32 s24, 0, 0x10000
	s_cmp_eq_u32 vcc_hi, 28
	s_cselect_b32 s43, s10, s1
	s_cselect_b32 s42, s11, s0
	v_add_u32_e32 v143, s24, v163
	s_cselect_b32 s1, s47, vcc_lo
	s_cselect_b32 s0, s49, s69
	s_add_i32 s55, 0, 0x14000
	ds_read_b128 v[144:147], v143
	ds_read_b128 v[148:151], v143 offset:1024
	ds_read_b128 v[152:155], v143 offset:2048
	ds_read_b128 v[156:159], v143 offset:3072
	v_add_u32_e32 v143, s55, v163
	ds_read_b128 v[184:187], v143
	ds_read_b128 v[188:191], v143 offset:1024
	ds_read_b128 v[192:195], v143 offset:2048
	ds_read_b128 v[196:199], v143 offset:3072
	v_lshl_add_u64 v[160:161], s[36:37], 0, v[138:139]
	s_add_i32 m0, s58, 0xc000
	ds_read_b128 v[200:203], v165
	ds_read_b128 v[204:207], v165 offset:1024
	ds_read_b128 v[208:211], v165 offset:2048
	ds_read_b128 v[232:235], v165 offset:3072
	ds_read_b128 v[236:239], v165 offset:4096
	ds_read_b128 v[240:243], v165 offset:5120
	ds_read_b128 v[244:247], v165 offset:6144
	ds_read_b128 v[248:251], v165 offset:7168
	global_load_lds_dwordx4 v[160:161], off
	v_lshl_add_u64 v[160:161], s[36:37], 0, v[140:141]
	s_add_i32 m0, s58, 0xe000
	s_nop 0
	global_load_lds_dwordx4 v[160:161], off
	s_waitcnt vmcnt(8)
	s_waitcnt lgkmcnt(0)
	s_barrier
	s_setprio 1
	s_waitcnt lgkmcnt(0)
	v_mfma_f32_16x16x32_bf16 v[124:127], v[144:147], v[200:203], v[124:127]
	v_mfma_f32_16x16x32_bf16 v[120:123], v[152:155], v[200:203], v[120:123]
	v_mfma_f32_16x16x32_bf16 v[108:111], v[144:147], v[208:211], v[108:111]
	v_mfma_f32_16x16x32_bf16 v[104:107], v[152:155], v[208:211], v[104:107]
	v_mfma_f32_16x16x32_bf16 v[92:95], v[144:147], v[236:239], v[92:95]
	v_mfma_f32_16x16x32_bf16 v[88:91], v[152:155], v[236:239], v[88:91]
	v_mfma_f32_16x16x32_bf16 v[76:79], v[144:147], v[244:247], v[76:79]
	v_mfma_f32_16x16x32_bf16 v[72:75], v[152:155], v[244:247], v[72:75]
	v_mfma_f32_16x16x32_bf16 v[124:127], v[148:151], v[204:207], v[124:127]
	v_mfma_f32_16x16x32_bf16 v[120:123], v[156:159], v[204:207], v[120:123]
	v_mfma_f32_16x16x32_bf16 v[108:111], v[148:151], v[232:235], v[108:111]
	v_mfma_f32_16x16x32_bf16 v[104:107], v[156:159], v[232:235], v[104:107]
	v_mfma_f32_16x16x32_bf16 v[92:95], v[148:151], v[240:243], v[92:95]
	v_mfma_f32_16x16x32_bf16 v[88:91], v[156:159], v[240:243], v[88:91]
	v_mfma_f32_16x16x32_bf16 v[76:79], v[148:151], v[248:251], v[76:79]
	v_mfma_f32_16x16x32_bf16 v[72:75], v[156:159], v[248:251], v[72:75]
	s_setprio 0
	s_setprio 1
	v_mfma_f32_16x16x32_bf16 v[116:119], v[184:187], v[200:203], v[116:119]
	v_mfma_f32_16x16x32_bf16 v[112:115], v[192:195], v[200:203], v[112:115]
	v_mfma_f32_16x16x32_bf16 v[100:103], v[184:187], v[208:211], v[100:103]
	v_mfma_f32_16x16x32_bf16 v[96:99], v[192:195], v[208:211], v[96:99]
	v_mfma_f32_16x16x32_bf16 v[84:87], v[184:187], v[236:239], v[84:87]
	v_mfma_f32_16x16x32_bf16 v[80:83], v[192:195], v[236:239], v[80:83]
	v_mfma_f32_16x16x32_bf16 v[68:71], v[184:187], v[244:247], v[68:71]
	v_mfma_f32_16x16x32_bf16 v[64:67], v[192:195], v[244:247], v[64:67]
	v_mfma_f32_16x16x32_bf16 v[116:119], v[188:191], v[204:207], v[116:119]
	v_mfma_f32_16x16x32_bf16 v[112:115], v[196:199], v[204:207], v[112:115]
	v_mfma_f32_16x16x32_bf16 v[100:103], v[188:191], v[232:235], v[100:103]
	v_mfma_f32_16x16x32_bf16 v[96:99], v[196:199], v[232:235], v[96:99]
	v_mfma_f32_16x16x32_bf16 v[84:87], v[188:191], v[240:243], v[84:87]
	v_mfma_f32_16x16x32_bf16 v[80:83], v[196:199], v[240:243], v[80:83]
	v_mfma_f32_16x16x32_bf16 v[68:71], v[188:191], v[248:251], v[68:71]
	v_mfma_f32_16x16x32_bf16 v[64:67], v[196:199], v[248:251], v[64:67]
	s_setprio 0
	s_barrier
	s_add_i32 s24, s24, s57
	v_lshl_add_u64 v[160:161], s[0:1], 0, v[132:133]
	s_mov_b32 m0, s24
	ds_read_b128 v[200:203], v165 offset:16384
	ds_read_b128 v[204:207], v165 offset:17408
	ds_read_b128 v[208:211], v165 offset:18432
	ds_read_b128 v[232:235], v165 offset:19456
	ds_read_b128 v[236:239], v165 offset:20480
	ds_read_b128 v[240:243], v165 offset:21504
	ds_read_b128 v[244:247], v165 offset:22528
	ds_read_b128 v[248:251], v165 offset:23552
	global_load_lds_dwordx4 v[160:161], off
	s_add_i32 m0, s24, 0x2000
	s_add_u32 s24, s0, 0x80000
	v_lshl_add_u64 v[166:167], s[0:1], 0, v[128:129]
	s_addc_u32 s25, s1, 0
	s_add_i32 s55, s55, s57
	global_load_lds_dwordx4 v[166:167], off
	v_lshl_add_u64 v[170:171], s[24:25], 0, v[132:133]
	s_mov_b32 m0, s55
	v_lshl_add_u64 v[212:213], s[42:43], 0, v[130:131]
	global_load_lds_dwordx4 v[170:171], off
	v_lshl_add_u64 v[170:171], s[24:25], 0, v[128:129]
	s_add_i32 m0, s55, 0x2000
	s_nop 0
	global_load_lds_dwordx4 v[170:171], off
	v_lshl_add_u64 v[170:171], s[42:43], 0, v[134:135]
	s_mov_b32 m0, s58
	s_nop 0
	global_load_lds_dwordx4 v[170:171], off
	s_mov_b32 m0, s59
	s_nop 0
	global_load_lds_dwordx4 v[212:213], off
	s_waitcnt vmcnt(8)
	s_waitcnt lgkmcnt(0)
	s_barrier
; #define PG8_STAGE(bufoff, gbase, voff) do { _Pragma("unroll") for (int _i = 0; _i < 2; ++_i) \
;         __builtin_amdgcn_global_load_lds((const unsigned*)((const char*)(gbase) + (voff)[_i]), (LAS unsigned*)(lds + (bufoff) + ldsw + _i * 8192), 16, 0, 0); } while (0)
; #define PG8_LDA(dst, b, h) do { _Pragma("unroll") for (int m = 0; m < 4; ++m) _Pragma("unroll") for (int k = 0; k < 2; ++k) dst[m][k] = *(const LAS bf16x8*)(lds + PG8_SA(b, h) + aoff + m * 2048 + k * 1024); } while (0)
; #define PG8_LDB(dst, b, h) do { _Pragma("unroll") for (int n = 0; n < 2; ++n) _Pragma("unroll") for (int k = 0; k < 2; ++k) dst[n][k] = *(const LAS bf16x8*)(lds + PG8_SB(b, h) + boff + n * 2048 + k * 1024); } while (0)
; #define PG8_MMA(ai, bj, At, Bt) do { __builtin_amdgcn_s_setprio(1); _Pragma("unroll") for (int m = 0; m < 4; ++m) _Pragma("unroll") for (int n = 0; n < 2; ++n) _Pragma("unroll") for (int k = 0; k < 2; ++k) \
;         acc[ai][bj][m][n] = __builtin_amdgcn_mfma_f32_16x16x32_bf16(Bt[n][k], At[m][k], acc[ai][bj][m][n], 0, 0, 0); __builtin_amdgcn_s_setprio(0); } while (0)
; #define PG8_WAIT_V(n) asm volatile("s_waitcnt vmcnt(" #n ")" ::: "memory")
; #define PG8_WAIT_L(n) asm volatile("s_waitcnt lgkmcnt(" #n ")" ::: "memory")
; #define PG8_BAR __builtin_amdgcn_s_barrier()
; #define PG8_SCHED __builtin_amdgcn_sched_barrier(0)
; template <class Epi>
; __device__ __forceinline__ void gemm_phase(LAS unsigned char* lds, const Gemm g, const StaticOrder& S, const Epi& E, const int tid) {
;     ...
;             PG8_WAIT_V(8); PG8_WAIT_L(0); PG8_BAR; PG8_MMA(1, 0, At, B0); PG8_MMA(1, 1, At, B1); PG8_BAR; PG8_SCHED;
;             PG8_LDB(B0, 1, 0); PG8_LDB(B1, 1, 1); PG8_SCHED; PG8_LDA(At, 1, 0); PG8_STAGE(PG8_SA(0, 1), a2 + hsA, voffA);
;             PG8_WAIT_V(8); PG8_WAIT_L(0); PG8_BAR; PG8_MMA(0, 0, At, B0); PG8_MMA(0, 1, At, B1); PG8_BAR; PG8_SCHED;
	s_setprio 1
	s_waitcnt lgkmcnt(0)
	v_mfma_f32_16x16x32_bf16 v[60:63], v[144:147], v[200:203], v[60:63]
	v_mfma_f32_16x16x32_bf16 v[56:59], v[152:155], v[200:203], v[56:59]
	v_mfma_f32_16x16x32_bf16 v[44:47], v[144:147], v[208:211], v[44:47]
	v_mfma_f32_16x16x32_bf16 v[40:43], v[152:155], v[208:211], v[40:43]
	v_mfma_f32_16x16x32_bf16 v[28:31], v[144:147], v[236:239], v[28:31]
	v_mfma_f32_16x16x32_bf16 v[24:27], v[152:155], v[236:239], v[24:27]
	v_mfma_f32_16x16x32_bf16 v[12:15], v[144:147], v[244:247], v[12:15]
	v_mfma_f32_16x16x32_bf16 v[8:11], v[152:155], v[244:247], v[8:11]
	v_mfma_f32_16x16x32_bf16 v[60:63], v[148:151], v[204:207], v[60:63]
	v_mfma_f32_16x16x32_bf16 v[56:59], v[156:159], v[204:207], v[56:59]
	v_mfma_f32_16x16x32_bf16 v[44:47], v[148:151], v[232:235], v[44:47]
	v_mfma_f32_16x16x32_bf16 v[40:43], v[156:159], v[232:235], v[40:43]
	v_mfma_f32_16x16x32_bf16 v[28:31], v[148:151], v[240:243], v[28:31]
	v_mfma_f32_16x16x32_bf16 v[24:27], v[156:159], v[240:243], v[24:27]
	v_mfma_f32_16x16x32_bf16 v[12:15], v[148:151], v[248:251], v[12:15]
	v_mfma_f32_16x16x32_bf16 v[8:11], v[156:159], v[248:251], v[8:11]
	s_setprio 0
	s_setprio 1
	v_mfma_f32_16x16x32_bf16 v[52:55], v[184:187], v[200:203], v[52:55]
	v_mfma_f32_16x16x32_bf16 v[48:51], v[192:195], v[200:203], v[48:51]
	v_mfma_f32_16x16x32_bf16 v[36:39], v[184:187], v[208:211], v[36:39]
	v_mfma_f32_16x16x32_bf16 v[32:35], v[192:195], v[208:211], v[32:35]
	v_mfma_f32_16x16x32_bf16 v[20:23], v[184:187], v[236:239], v[20:23]
	v_mfma_f32_16x16x32_bf16 v[16:19], v[192:195], v[236:239], v[16:19]
	v_mfma_f32_16x16x32_bf16 v[4:7], v[184:187], v[244:247], v[4:7]
	v_mfma_f32_16x16x32_bf16 v[0:3], v[192:195], v[244:247], v[0:3]
	v_mfma_f32_16x16x32_bf16 v[52:55], v[188:191], v[204:207], v[52:55]
	v_mfma_f32_16x16x32_bf16 v[48:51], v[196:199], v[204:207], v[48:51]
	v_mfma_f32_16x16x32_bf16 v[36:39], v[188:191], v[232:235], v[36:39]
	v_mfma_f32_16x16x32_bf16 v[32:35], v[196:199], v[232:235], v[32:35]
	v_mfma_f32_16x16x32_bf16 v[20:23], v[188:191], v[240:243], v[20:23]
	v_mfma_f32_16x16x32_bf16 v[16:19], v[196:199], v[240:243], v[16:19]
	v_mfma_f32_16x16x32_bf16 v[4:7], v[188:191], v[248:251], v[4:7]
	v_mfma_f32_16x16x32_bf16 v[0:3], v[196:199], v[248:251], v[0:3]
	s_setprio 0
	s_barrier
	s_add_i32 s55, 0, 0x18000
	v_add_u32_e32 v143, s55, v163
	s_add_i32 s67, 0, 0x1c000
	ds_read_b128 v[144:147], v143
	ds_read_b128 v[148:151], v143 offset:1024
	ds_read_b128 v[152:155], v143 offset:2048
	ds_read_b128 v[156:159], v143 offset:3072
	v_add_u32_e32 v143, s67, v163
	ds_read_b128 v[184:187], v143
	ds_read_b128 v[188:191], v143 offset:1024
	ds_read_b128 v[192:195], v143 offset:2048
	ds_read_b128 v[196:199], v143 offset:3072
	s_add_u32 s24, s42, 0x80000
	s_addc_u32 s25, s43, 0
	s_mov_b32 m0, s27
	v_lshl_add_u64 v[172:173], s[24:25], 0, v[134:135]
	ds_read_b128 v[200:203], v165 offset:32768
	ds_read_b128 v[204:207], v165 offset:33792
	ds_read_b128 v[208:211], v165 offset:34816
	ds_read_b128 v[232:235], v165 offset:35840
	ds_read_b128 v[236:239], v165 offset:36864
	ds_read_b128 v[240:243], v165 offset:37888
	ds_read_b128 v[244:247], v165 offset:38912
	ds_read_b128 v[248:251], v165 offset:39936
	global_load_lds_dwordx4 v[172:173], off
	v_lshl_add_u64 v[172:173], s[24:25], 0, v[130:131]
	s_mov_b32 m0, s96
	s_nop 0
	global_load_lds_dwordx4 v[172:173], off
	s_waitcnt vmcnt(8)
	s_waitcnt lgkmcnt(0)
	s_barrier
	s_setprio 1
	s_waitcnt lgkmcnt(0)
	v_mfma_f32_16x16x32_bf16 v[124:127], v[144:147], v[200:203], v[124:127]
	v_mfma_f32_16x16x32_bf16 v[120:123], v[152:155], v[200:203], v[120:123]
	v_mfma_f32_16x16x32_bf16 v[108:111], v[144:147], v[208:211], v[108:111]
	v_mfma_f32_16x16x32_bf16 v[104:107], v[152:155], v[208:211], v[104:107]
	v_mfma_f32_16x16x32_bf16 v[92:95], v[144:147], v[236:239], v[92:95]
	v_mfma_f32_16x16x32_bf16 v[88:91], v[152:155], v[236:239], v[88:91]
	v_mfma_f32_16x16x32_bf16 v[76:79], v[144:147], v[244:247], v[76:79]
	v_mfma_f32_16x16x32_bf16 v[72:75], v[152:155], v[244:247], v[72:75]
	v_mfma_f32_16x16x32_bf16 v[124:127], v[148:151], v[204:207], v[124:127]
	v_mfma_f32_16x16x32_bf16 v[120:123], v[156:159], v[204:207], v[120:123]
	v_mfma_f32_16x16x32_bf16 v[108:111], v[148:151], v[232:235], v[108:111]
	v_mfma_f32_16x16x32_bf16 v[104:107], v[156:159], v[232:235], v[104:107]
	v_mfma_f32_16x16x32_bf16 v[92:95], v[148:151], v[240:243], v[92:95]
	v_mfma_f32_16x16x32_bf16 v[88:91], v[156:159], v[240:243], v[88:91]
	v_mfma_f32_16x16x32_bf16 v[76:79], v[148:151], v[248:251], v[76:79]
	v_mfma_f32_16x16x32_bf16 v[72:75], v[156:159], v[248:251], v[72:75]
	s_setprio 0
	s_setprio 1
	v_mfma_f32_16x16x32_bf16 v[116:119], v[184:187], v[200:203], v[116:119]
	v_mfma_f32_16x16x32_bf16 v[112:115], v[192:195], v[200:203], v[112:115]
	v_mfma_f32_16x16x32_bf16 v[100:103], v[184:187], v[208:211], v[100:103]
	v_mfma_f32_16x16x32_bf16 v[96:99], v[192:195], v[208:211], v[96:99]
	v_mfma_f32_16x16x32_bf16 v[84:87], v[184:187], v[236:239], v[84:87]
	v_mfma_f32_16x16x32_bf16 v[80:83], v[192:195], v[236:239], v[80:83]
	v_mfma_f32_16x16x32_bf16 v[68:71], v[184:187], v[244:247], v[68:71]
	v_mfma_f32_16x16x32_bf16 v[64:67], v[192:195], v[244:247], v[64:67]
	v_mfma_f32_16x16x32_bf16 v[116:119], v[188:191], v[204:207], v[116:119]
	v_mfma_f32_16x16x32_bf16 v[112:115], v[196:199], v[204:207], v[112:115]
	v_mfma_f32_16x16x32_bf16 v[100:103], v[188:191], v[232:235], v[100:103]
	v_mfma_f32_16x16x32_bf16 v[96:99], v[196:199], v[232:235], v[96:99]
	v_mfma_f32_16x16x32_bf16 v[84:87], v[188:191], v[240:243], v[84:87]
	v_mfma_f32_16x16x32_bf16 v[80:83], v[196:199], v[240:243], v[80:83]
	v_mfma_f32_16x16x32_bf16 v[68:71], v[188:191], v[248:251], v[68:71]
	v_mfma_f32_16x16x32_bf16 v[64:67], v[196:199], v[248:251], v[64:67]
	s_setprio 0
	s_barrier
; #define PG8_STAGE(bufoff, gbase, voff) do { _Pragma("unroll") for (int _i = 0; _i < 2; ++_i) \
;         __builtin_amdgcn_global_load_lds((const unsigned*)((const char*)(gbase) + (voff)[_i]), (LAS unsigned*)(lds + (bufoff) + ldsw + _i * 8192), 16, 0, 0); } while (0)
; #define PG8_LDA(dst, b, h) do { _Pragma("unroll") for (int m = 0; m < 4; ++m) _Pragma("unroll") for (int k = 0; k < 2; ++k) dst[m][k] = *(const LAS bf16x8*)(lds + PG8_SA(b, h) + aoff + m * 2048 + k * 1024); } while (0)
; #define PG8_MMA(ai, bj, At, Bt) do { __builtin_amdgcn_s_setprio(1); _Pragma("unroll") for (int m = 0; m < 4; ++m) _Pragma("unroll") for (int n = 0; n < 2; ++n) _Pragma("unroll") for (int k = 0; k < 2; ++k) \
;         acc[ai][bj][m][n] = __builtin_amdgcn_mfma_f32_16x16x32_bf16(Bt[n][k], At[m][k], acc[ai][bj][m][n], 0, 0, 0); __builtin_amdgcn_s_setprio(0); } while (0)
; #define PG8_WAIT_V(n) asm volatile("s_waitcnt vmcnt(" #n ")" ::: "memory")
; #define PG8_WAIT_L(n) asm volatile("s_waitcnt lgkmcnt(" #n ")" ::: "memory")
; #define PG8_BAR __builtin_amdgcn_s_barrier()
; #define PG8_SCHED __builtin_amdgcn_sched_barrier(0)
; template <class Epi>
; __device__ __forceinline__ void gemm_phase(LAS unsigned char* lds, const Gemm g, const StaticOrder& S, const Epi& E, const int tid) {
;     ...
;             PG8_LDA(At, 1, 1); PG8_STAGE(PG8_SB(1, 0), b3, voffB); PG8_STAGE(PG8_SB(1, 1), b3 + hsB, voffB); PG8_STAGE(PG8_SA(1, 0), a3, voffA);
;             PG8_WAIT_V(8); PG8_WAIT_L(0); PG8_BAR; PG8_MMA(1, 0, At, B0); PG8_MMA(1, 1, At, B1); PG8_BAR; PG8_SCHED;
;         }
;         if (wr == 0) PG8_BAR;
;         E(acc, cur, wr, wc, fr, fq);
;     __device__ __forceinline__ void operator()(f32x4 (&acc)[2][2][4][2], const Unit& u, int wr, int wc, int fr, int fq) const {
;     ...
;         bf16* dst; int ld, c0; bool sg = false;
;         if (u.pn < 12) { dst = UA; ld = 3072; c0 = u.pn * 256; }
;         else if (u.pn < 28) { dst = UB; ld = 4096; c0 = (u.pn - 12) * 256; }
;         else if (u.pn < 42) { dst = UC; ld = 3584; c0 = (u.pn - 28) * 256; }
;         else { dst = UG; ld = 6144; c0 = (u.pn - 42) * 256; sg = true; }
	s_add_i32 s24, s55, s57
	v_lshl_add_u64 v[160:161], v[160:161], 0, s[28:29]
	s_mov_b32 m0, s24
	ds_read_b128 v[200:203], v165 offset:49152
	ds_read_b128 v[204:207], v165 offset:50176
	ds_read_b128 v[208:211], v165 offset:51200
	ds_read_b128 v[232:235], v165 offset:52224
	ds_read_b128 v[236:239], v165 offset:53248
	ds_read_b128 v[240:243], v165 offset:54272
	ds_read_b128 v[244:247], v165 offset:55296
	ds_read_b128 v[248:251], v165 offset:56320
	global_load_lds_dwordx4 v[160:161], off
	s_add_i32 m0, s24, 0x2000
	s_add_u32 s0, s0, 0x80080
	v_lshl_add_u64 v[160:161], v[166:167], 0, s[28:29]
	s_addc_u32 s1, s1, 0
	s_add_i32 s24, s67, s57
	global_load_lds_dwordx4 v[160:161], off
	v_lshl_add_u64 v[160:161], s[0:1], 0, v[132:133]
	s_mov_b32 m0, s24
	s_nop 0
	global_load_lds_dwordx4 v[160:161], off
	v_lshl_add_u64 v[160:161], s[0:1], 0, v[128:129]
	s_add_i32 m0, s24, 0x2000
	s_nop 0
	global_load_lds_dwordx4 v[160:161], off
	v_lshl_add_u64 v[160:161], v[170:171], 0, s[28:29]
	s_mov_b32 m0, s6
	s_nop 0
	global_load_lds_dwordx4 v[160:161], off
	v_lshl_add_u64 v[160:161], v[212:213], 0, s[28:29]
	s_mov_b32 m0, s7
	s_nop 0
	global_load_lds_dwordx4 v[160:161], off
	s_waitcnt vmcnt(8)
	s_waitcnt lgkmcnt(0)
	s_barrier
	s_setprio 1
	s_waitcnt lgkmcnt(0)
	v_mfma_f32_16x16x32_bf16 v[60:63], v[144:147], v[200:203], v[60:63]
	v_mfma_f32_16x16x32_bf16 v[56:59], v[152:155], v[200:203], v[56:59]
	v_mfma_f32_16x16x32_bf16 v[44:47], v[144:147], v[208:211], v[44:47]
	v_mfma_f32_16x16x32_bf16 v[40:43], v[152:155], v[208:211], v[40:43]
	v_mfma_f32_16x16x32_bf16 v[28:31], v[144:147], v[236:239], v[28:31]
	v_mfma_f32_16x16x32_bf16 v[24:27], v[152:155], v[236:239], v[24:27]
	v_mfma_f32_16x16x32_bf16 v[12:15], v[144:147], v[244:247], v[12:15]
	v_mfma_f32_16x16x32_bf16 v[8:11], v[152:155], v[244:247], v[8:11]
	v_mfma_f32_16x16x32_bf16 v[60:63], v[148:151], v[204:207], v[60:63]
	v_mfma_f32_16x16x32_bf16 v[56:59], v[156:159], v[204:207], v[56:59]
	v_mfma_f32_16x16x32_bf16 v[44:47], v[148:151], v[232:235], v[44:47]
	v_mfma_f32_16x16x32_bf16 v[40:43], v[156:159], v[232:235], v[40:43]
	v_mfma_f32_16x16x32_bf16 v[28:31], v[148:151], v[240:243], v[28:31]
	v_mfma_f32_16x16x32_bf16 v[24:27], v[156:159], v[240:243], v[24:27]
	v_mfma_f32_16x16x32_bf16 v[12:15], v[148:151], v[248:251], v[12:15]
	v_mfma_f32_16x16x32_bf16 v[8:11], v[156:159], v[248:251], v[8:11]
	s_setprio 0
	s_setprio 1
	v_mfma_f32_16x16x32_bf16 v[52:55], v[184:187], v[200:203], v[52:55]
	v_mfma_f32_16x16x32_bf16 v[48:51], v[192:195], v[200:203], v[48:51]
	v_mfma_f32_16x16x32_bf16 v[36:39], v[184:187], v[208:211], v[36:39]
	v_mfma_f32_16x16x32_bf16 v[32:35], v[192:195], v[208:211], v[32:35]
	v_mfma_f32_16x16x32_bf16 v[20:23], v[184:187], v[236:239], v[20:23]
	v_mfma_f32_16x16x32_bf16 v[16:19], v[192:195], v[236:239], v[16:19]
	v_mfma_f32_16x16x32_bf16 v[4:7], v[184:187], v[244:247], v[4:7]
	v_mfma_f32_16x16x32_bf16 v[0:3], v[192:195], v[244:247], v[0:3]
	v_mfma_f32_16x16x32_bf16 v[52:55], v[188:191], v[204:207], v[52:55]
	v_mfma_f32_16x16x32_bf16 v[48:51], v[196:199], v[204:207], v[48:51]
	v_mfma_f32_16x16x32_bf16 v[36:39], v[188:191], v[232:235], v[36:39]
	v_mfma_f32_16x16x32_bf16 v[32:35], v[196:199], v[232:235], v[32:35]
	v_mfma_f32_16x16x32_bf16 v[20:23], v[188:191], v[240:243], v[20:23]
	v_mfma_f32_16x16x32_bf16 v[16:19], v[196:199], v[240:243], v[16:19]
	v_mfma_f32_16x16x32_bf16 v[4:7], v[188:191], v[248:251], v[4:7]
	v_mfma_f32_16x16x32_bf16 v[0:3], v[196:199], v[248:251], v[0:3]
	s_setprio 0
	s_barrier
	s_add_i32 vcc_hi, vcc_hi, 2
	s_add_u32 s36, s36, 0x100
	s_addc_u32 s37, s37, 0
	s_add_u32 s69, s69, 0x100
	s_addc_u32 vcc_lo, vcc_lo, 0
	s_cmp_gt_u32 vcc_hi, 29
	s_cbranch_scc0 .LBB0_354
.LBB0_357:
	v_lshl_add_u32 v166, s60, 8, v162
	s_cmp_gt_i32 s45, 7
	s_mov_b64 s[0:1], -1
	s_cbranch_scc0 .LBB0_421
	s_cmp_gt_u32 s45, 11
	s_mov_b64 s[10:11], -1
	s_cbranch_scc0 .LBB0_368
	s_lshl_b32 s49, s45, 8
	s_cmp_gt_u32 s45, 27
	s_cbranch_scc0 .LBB0_365
	s_mov_b64 s[0:1], -1
	s_cmp_gt_u32 s45, 41
	s_cbranch_scc0 .LBB0_362
	s_add_i32 s47, s49, 0xffffd600
	s_mov_b64 s[10:11], 0

; #define PG8_BAR __builtin_amdgcn_s_barrier()
; template <class Epi>
; __device__ __forceinline__ void gemm_phase(LAS unsigned char* lds, const Gemm g, const StaticOrder& S, const Epi& E, const int tid) {
;     ...
;         if (wr == 0) PG8_BAR;
.LBB0_423:
	s_and_b64 vcc, exec, s[34:35]
	s_cbranch_vccz .Lepi_win_nb
	s_barrier

; #define LAS __attribute__((address_space(3)))
; __device__ __forceinline__ void attn_unit(LAS unsigned char* lds, const bf16* UA, bf16* Y, int bl, int h, int qb,
;                                           const float* qkg, const float* rel_bias, const float* lamv, const float* dgain, float lam_init, int tid, int wave, int lane) {
;     ...
;     float gqm = fabsf(qkg[lane]), gkm = fabsf(qkg[64 + lane]), bm = lane < 32 ? fabsf(rel_bias[lane * 8 + h]) : 0.f;
;     gqm = wave_max(gqm); gkm = wave_max(gkm); bm = wave_max(bm);
;     const float Mb = (8.0f * gqm * gkm * 1.02f + bm) * LOG2E + 1.0f;
;     const float s01 = wave_sum(lamv[lane] * lamv[64 + lane]), s23 = wave_sum(lamv[128 + lane] * lamv[192 + lane]);
;     const float lam = __expf(s01) - __expf(s23) + lam_init;
;     const float cb_far = rel_bias[15 * 8 + h] * LOG2E - Mb;
;     LAS float* tbl = (LAS float*)(lds + AT_TBL);
;     if (tid < 255) { const int rel = tid - 191, n = rel < 0 ? -rel : rel;
;         int bk = n < 8 ? n : (8 + (31 - __clz(n * n)) - 6); if (bk > 15) bk = 15; if (rel > 0) bk += 16;
;         tbl[tid] = (rel_bias[bk * 8 + h] - rel_bias[15 * 8 + h]) * LOG2E; }
;     const int q0 = qb * 128 + wq * 32, qc = qb * 2 + (wq >> 1);
;     bf16x8 qr[2][2];
; #pragma unroll
;     for (int qb2 = 0; qb2 < 2; ++qb2)
; #pragma unroll
;         for (int ks = 0; ks < 2; ++ks) qr[qb2][ks] = *(const bf16x8*)(UA + (size_t)(bl * SEQ + q0 + 16 * qb2 + x) * 3072 + h * 128 + m * 64 + 32 * ks + 8 * g);
;     f32x4 O[8][2];
; #pragma unroll
;     for (int db = 0; db < 8; ++db)
; #pragma unroll
;         for (int qb2 = 0; qb2 < 2; ++qb2) O[db][qb2] = (f32x4){0.f, 0.f, 0.f, 0.f};
;     float lsum[2] = {0.f, 0.f};
;     f32x4 CI;
; #pragma unroll
;     for (int r = 0; r < 4; ++r) { float c = cb_far; asm volatile("" : "+v"(c)); CI[r] = c; }
;     const int NT = 2 * qb + 2;
;     const bf16* ksrc = UA + (size_t)(bl * SEQ) * 3072 + 1024 + h * 128;
;     const bf16* vsrc = UA + (size_t)(bl * SEQ) * 3072 + 2048 + h * 128;
;     u32x4 rk[2], rv[2];
;     ...
;     AT_LOAD(0); AT_STORE(0);
;     __syncthreads();
;     const int koff = x * AT_KROW + m * 128 + g * 16;
;     const int voff = (4 * g + (x >> 2)) * AT_VROW + (4 * (x & 3)) * 2;
.LBB0_522:
	s_or_b64 exec, exec, s[0:1]
	v_max_f32_e32 v1, v1, v1
	v_max_f32_e32 v0, v0, v0
	v_max_f32_e32 v0, v0, v1
	v_max_f32_e32 v1, v3, v3
	v_max_f32_e32 v2, v2, v2
	v_max_f32_e32 v1, v2, v1
	v_max_f32_e32 v2, v5, v5
	v_max_f32_e32 v3, v4, v4
	v_mul_f32_e32 v0, 0x41000000, v0
	v_max_f32_e32 v2, v3, v2
	v_mul_f32_e32 v0, v0, v1
	v_fmac_f32_e32 v2, 0x3f828f5c, v0
	s_mov_b32 s0, 0x3fb8aa3b
	v_fma_f32 v0, v2, s0, 1.0
	s_waitcnt vmcnt(0)
	v_fma_f32 v67, v6, s0, -v0
	s_add_i32 s0, s56, 0xfffffcc0
	s_not_b32 s1, s0
	s_bfe_u32 s36, s1, 0x50003
	s_bfe_u32 s10, s6, 0x20006
	s_lshr_b32 s24, s0, 8
	s_lshl_b32 s0, s36, 7
	s_lshl_b32 s1, s10, 5
	s_lshr_b32 s12, s6, 6
	s_ashr_i32 s7, s6, 8
	s_or_b32 s1, s1, s0
	s_lshl_b32 s6, s24, 12
	v_and_b32_e32 v146, 15, v186
	s_or_b32 s6, s1, s6
	s_bfe_u32 s27, s12, 0x10001
	v_or_b32_e32 v2, s6, v146
	s_lshl_b32 s6, s11, 7
	s_lshl_b32 s11, s11, 8
	v_readlane_b32 s14, v254, 23
	v_readlane_b32 s15, v254, 24
	s_add_u32 s25, s14, s11
	s_addc_u32 s37, s15, 0
	s_lshl_b32 s12, s7, 6
	s_ashr_i32 s13, s12, 31
	s_lshl_b64 s[12:13], s[12:13], 1
	s_add_u32 s12, s25, s12
	s_addc_u32 s13, s37, s13
	v_and_b32_e32 v16, 48, v187
	v_mov_b32_e32 v17, v169
	v_lshl_add_u64 v[0:1], s[12:13], 0, v[16:17]
	s_movk_i32 s12, 0xc00
	v_mul_lo_u32 v168, v2, s12
	v_lshl_add_u64 v[0:1], v[168:169], 1, v[0:1]
	s_mov_b64 s[12:13], 0x18000
	v_lshl_add_u64 v[2:3], v[0:1], 0, s[12:13]
	s_mov_b32 s12, 0x18000
	s_mul_i32 s60, s24, 0xc00000
	global_load_dwordx4 v[72:75], v[0:1], off
	global_load_dwordx4 v[68:71], v[0:1], off offset:64
	v_add_co_u32_e32 v0, vcc, s12, v0
	s_lshl_b32 s37, s36, 1
	s_lshl_b64 s[12:13], s[60:61], 1
	s_add_u32 s24, s14, s12
	v_addc_co_u32_e32 v1, vcc, 0, v1, vcc
	s_addc_u32 s25, s15, s13
	global_load_dwordx4 v[80:83], v[0:1], off
	global_load_dwordx4 v[76:79], v[2:3], off offset:64
	s_add_u32 s24, s24, s11
	v_lshlrev_b32_e32 v0, 4, v186
	s_addc_u32 s25, s25, 0
	v_and_b32_e32 v18, 0xf0, v0
	v_mov_b32_e32 v19, v169
	v_lshl_add_u64 v[8:9], s[24:25], 0, v[18:19]
	s_mov_b64 s[14:15], 0x1000
	v_add_u32_e32 v12, 0x200, v186
	v_lshl_add_u64 v[10:11], v[8:9], 0, s[14:15]
	v_ashrrev_i32_e32 v17, 4, v186
	v_ashrrev_i32_e32 v19, 4, v12
	v_mov_b32_e32 v64, v67
	v_mov_b32_e32 v65, v67
	v_mov_b32_e32 v66, v67
	v_mad_i64_i32 v[0:1], s[24:25], v17, s97, v[8:9]
	v_mad_i64_i32 v[4:5], s[24:25], v17, s97, v[10:11]
	v_mad_i64_i32 v[8:9], s[24:25], v19, s97, v[8:9]
	v_mad_i64_i32 v[12:13], s[24:25], v19, s97, v[10:11]
	global_load_dwordx4 v[0:3], v[0:1], off offset:2048
	s_nop 0
	global_load_dwordx4 v[4:7], v[4:5], off
	s_nop 0
	global_load_dwordx4 v[8:11], v[8:9], off offset:2048
	s_nop 0
	global_load_dwordx4 v[12:15], v[12:13], off
	s_movk_i32 s14, 0x120
	v_mul_lo_u32 v147, v17, s14
	v_add_u32_e32 v148, 0, v18
	v_mul_lo_u32 v149, v19, s14
	v_add_u32_e32 v18, v148, v147
	s_lshl_b32 s24, s7, 7
	v_add_u32_e32 v20, v148, v149
	s_add_i32 s24, s24, 0
	s_lshl_b32 s36, s36, 9
	s_or_b32 s27, s27, s37
	v_readlane_b32 s16, v252, 11
	v_readlane_b32 s18, v252, 13
	v_readlane_b32 s19, v252, 14
	s_mov_b32 s11, 0
	v_mov_b32_e32 v132, v169
	v_mov_b32_e32 v133, v169
	s_mov_b32 s42, s27
	v_readlane_b32 s17, v252, 12
	v_readlane_b32 s20, v252, 15
	v_readlane_b32 s21, v252, 16
	v_readlane_b32 s22, v252, 17
	v_readlane_b32 s23, v252, 18
	s_waitcnt vmcnt(3)
	ds_write_b128 v18, v[0:3]
	s_waitcnt vmcnt(2)
	ds_write_b128 v18, v[4:7] offset:36864
	s_waitcnt vmcnt(1)
	ds_write_b128 v20, v[8:11]
	s_waitcnt vmcnt(0)
	ds_write_b128 v20, v[12:15] offset:36864
	v_mul_u32_u24_e32 v0, 0x120, v146
	v_and_b32_e32 v1, 48, v186
	v_add3_u32 v150, s24, v0, v1
	v_lshlrev_b32_e32 v0, 2, v146
	v_sub_u32_e32 v0, v16, v0
	s_lshl_b32 s24, s10, 7
	v_lshrrev_b32_e32 v2, 2, v187
	v_subrev_u32_e32 v0, s24, v0
	v_and_b32_e32 v144, 12, v2
	v_bfe_u32 v2, v186, 2, 2
	v_subrev_u32_e32 v0, s36, v0
	v_or_b32_e32 v2, v144, v2
	v_lshlrev_b32_e32 v3, 3, v187
	v_add_u32_e32 v151, 0, v0
	v_mad_i64_i32 v[0:1], s[24:25], v17, s97, 0
	v_mul_u32_u24_e32 v2, 0x120, v2
	v_and_b32_e32 v3, 24, v3
	s_lshl_b32 s24, s56, 8
	v_add3_u32 v145, 0, v2, v3
	s_and_b32 s37, s24, 0x700
	v_lshlrev_b32_e32 v2, 4, v146
	v_or3_b32 v0, v0, s37, v2
	v_lshl_add_u64 v[134:135], s[18:19], 0, v[0:1]
	v_mad_i64_i32 v[0:1], s[24:25], v19, s97, 0
	v_or3_b32 v0, v0, s37, v2
	v_mov_b32_e32 v2, v169
	v_mov_b32_e32 v3, v169
	v_lshl_add_u64 v[136:137], s[18:19], 0, v[0:1]
	v_mov_b32_e32 v0, v169
	v_mov_b32_e32 v1, v169
	v_mov_b64_e32 v[6:7], v[2:3]
	v_mov_b64_e32 v[10:11], v[2:3]
	v_mov_b64_e32 v[30:31], v[2:3]
	v_mov_b64_e32 v[22:23], v[2:3]
	v_mov_b64_e32 v[34:35], v[2:3]
	v_mov_b64_e32 v[26:27], v[2:3]
	v_mov_b64_e32 v[42:43], v[2:3]
	v_mov_b64_e32 v[38:39], v[2:3]
	v_mov_b64_e32 v[46:47], v[2:3]
	v_mov_b64_e32 v[50:51], v[2:3]
	v_mov_b64_e32 v[54:55], v[2:3]
	v_mov_b64_e32 v[58:59], v[2:3]
	v_mov_b64_e32 v[62:63], v[2:3]
	v_mov_b64_e32 v[18:19], v[2:3]
	v_mov_b64_e32 v[14:15], v[2:3]
	s_movk_i32 s37, 0xff00
	v_mov_b64_e32 v[4:5], v[0:1]
	v_mov_b64_e32 v[8:9], v[0:1]
	v_mov_b64_e32 v[28:29], v[0:1]
	v_mov_b64_e32 v[20:21], v[0:1]
	v_mov_b64_e32 v[32:33], v[0:1]
	v_mov_b64_e32 v[24:25], v[0:1]
	v_mov_b64_e32 v[40:41], v[0:1]
	v_mov_b64_e32 v[36:37], v[0:1]
	v_mov_b64_e32 v[44:45], v[0:1]
	v_mov_b64_e32 v[48:49], v[0:1]
	v_mov_b64_e32 v[52:53], v[0:1]
	v_mov_b64_e32 v[56:57], v[0:1]
	v_mov_b64_e32 v[60:61], v[0:1]
	v_mov_b64_e32 v[16:17], v[0:1]
	v_mov_b64_e32 v[12:13], v[0:1]
	s_waitcnt lgkmcnt(0)
	s_barrier
	v_lshl_add_u64 v[232:233], v[134:135], 0, s[12:13]
	s_mov_b32 s24, 0x23860000
	v_add_co_u32_e32 v234, vcc, s24, v232
	v_lshl_add_u64 v[240:241], v[136:137], 0, s[12:13]
	s_nop 0
	v_addc_co_u32_e32 v235, vcc, 0, v233, vcc
	v_add_co_u32_e32 v236, vcc, 0x23861000, v232
	s_nop 0
	s_nop 0
	v_addc_co_u32_e32 v237, vcc, 0, v233, vcc
	v_add_co_u32_e32 v242, vcc, 0x23860000, v240
	global_load_dwordx4 v[232:235], v[234:235], off offset:2048
	s_nop 0
	global_load_dwordx4 v[236:239], v[236:237], off
	v_addc_co_u32_e32 v243, vcc, 0, v241, vcc
	v_add_co_u32_e32 v244, vcc, 0x23861000, v240
	s_nop 0
	s_nop 0
	v_addc_co_u32_e32 v245, vcc, 0, v241, vcc
	global_load_dwordx4 v[240:243], v[242:243], off offset:2048
	s_nop 0
	global_load_dwordx4 v[244:247], v[244:245], off
	v_lshl_add_u64 v[134:135], v[134:135], 0, s[52:53]
	v_lshl_add_u64 v[136:137], v[136:137], 0, s[52:53]
	s_branch .LBB0_525
; #define LAS __attribute__((address_space(3)))
; __device__ __forceinline__ unsigned cvt_pk_bf16(float lo, float hi) { unsigned r; asm volatile("v_cvt_pk_bf16_f32 %0, %1, %2" : "=v"(r) : "v"(lo), "v"(hi)); return r; }
; __device__ __forceinline__ float fast_exp2(float x) { return __builtin_amdgcn_exp2f(x); }
; __device__ __forceinline__ void attn_unit(LAS unsigned char* lds, const bf16* UA, bf16* Y, int bl, int h, int qb,
;                                           const float* qkg, const float* rel_bias, const float* lamv, const float* dgain, float lam_init, int tid, int wave, int lane) {
;     ...
;             u32x4 P[2][2];
; #pragma unroll
;             for (int kb = 0; kb < 4; ++kb)
; #pragma unroll
;                 for (int qb2 = 0; qb2 < 2; ++qb2) {
; #pragma unroll
;                     for (int i = 0; i < 4; ++i) { S[kb][qb2][i] = fast_exp2(S[kb][qb2][i]); lsum[qb2] += S[kb][qb2][i]; }
;                     const unsigned w0 = cvt_pk_bf16(S[kb][qb2][0], S[kb][qb2][1]), w1 = cvt_pk_bf16(S[kb][qb2][2], S[kb][qb2][3]);
;                     if (kb & 1) { P[kb >> 1][qb2].z = w0; P[kb >> 1][qb2].w = w1; } else { P[kb >> 1][qb2].x = w0; P[kb >> 1][qb2].y = w1; }
;                 }
; #pragma unroll
;             for (int s2 = 0; s2 < 2; ++s2) {
; #pragma unroll
;                 for (int dq = 0; dq < 2; ++dq) {
;                     bf16x8 vf[4];
; #pragma unroll
;                     for (int e = 0; e < 4; ++e) { const LAS unsigned char* vp = Vb + voff + (32 * s2) * AT_VROW + (16 * (4 * dq + e)) * 2;
;                         const s16x4 lo = __builtin_bit_cast(s16x4, __builtin_amdgcn_ds_read_tr16_b64_v4i16((LAS v4i16_t*)vp)), hi4 = __builtin_bit_cast(s16x4, __builtin_amdgcn_ds_read_tr16_b64_v4i16((LAS v4i16_t*)(vp + 16 * AT_VROW)));
;                         vf[e] = (bf16x8){lo[0], lo[1], lo[2], lo[3], hi4[0], hi4[1], hi4[2], hi4[3]}; }
;                     __builtin_amdgcn_s_setprio(1);
; #pragma unroll
;                     for (int e = 0; e < 4; ++e)
; #pragma unroll
;                         for (int qb2 = 0; qb2 < 2; ++qb2) O[4 * dq + e][qb2] = __builtin_amdgcn_mfma_f32_16x16x32_bf16(vf[e], __builtin_bit_cast(bf16x8, P[s2][qb2]), O[4 * dq + e][qb2], 0, 0, 0);
;                     __builtin_amdgcn_s_setprio(0);
;                     __builtin_amdgcn_sched_barrier(0);
;                 }
;             }
.LBB0_523:
	v_exp_f32_e32 v153, v128
	v_exp_f32_e32 v152, v124
	v_exp_f32_e32 v155, v129
	v_exp_f32_e32 v154, v125
	v_exp_f32_e32 v157, v130
	v_exp_f32_e32 v156, v126
	v_exp_f32_e32 v159, v131
	v_exp_f32_e32 v158, v127
	v_exp_f32_e32 v125, v120
	v_exp_f32_e32 v124, v116
	v_exp_f32_e32 v126, v117
	v_pk_add_f32 v[116:117], v[132:133], v[152:153]
	v_exp_f32_e32 v127, v121
	v_pk_add_f32 v[116:117], v[154:155], v[116:117]
	v_exp_f32_e32 v161, v122
	v_pk_add_f32 v[116:117], v[156:157], v[116:117]
	v_exp_f32_e32 v160, v118
	v_exp_f32_e32 v163, v123
	v_pk_add_f32 v[116:117], v[158:159], v[116:117]
	v_exp_f32_e32 v162, v119
	v_pk_add_f32 v[116:117], v[124:125], v[116:117]
	v_exp_f32_e32 v119, v112
	v_exp_f32_e32 v118, v108
	v_cvt_pk_bf16_f32 v128, v153, v155
	v_cvt_pk_bf16_f32 v129, v157, v159
	v_cvt_pk_bf16_f32 v120, v152, v154
	v_cvt_pk_bf16_f32 v121, v156, v158
	v_cvt_pk_bf16_f32 v130, v125, v127
	v_cvt_pk_bf16_f32 v131, v161, v163
	v_pk_add_f32 v[116:117], v[126:127], v[116:117]
	v_exp_f32_e32 v125, v113
	v_cvt_pk_bf16_f32 v122, v124, v126
	v_exp_f32_e32 v124, v109
	v_exp_f32_e32 v127, v114
	v_exp_f32_e32 v126, v110
	v_exp_f32_e32 v152, v100
	v_exp_f32_e32 v154, v101
	v_pk_add_f32 v[100:101], v[160:161], v[116:117]
	v_exp_f32_e32 v133, v115
	v_exp_f32_e32 v132, v111
	v_pk_add_f32 v[100:101], v[162:163], v[100:101]
	v_cvt_pk_bf16_f32 v123, v160, v162
	v_add_u32_e32 v188, s44, v145
	v_pk_add_f32 v[100:101], v[118:119], v[100:101]
	v_cvt_pk_bf16_f32 v112, v119, v125
	v_cvt_pk_bf16_f32 v113, v127, v133
	v_exp_f32_e32 v153, v104
	v_pk_add_f32 v[100:101], v[124:125], v[100:101]
	v_exp_f32_e32 v155, v105
	v_pk_add_f32 v[100:101], v[126:127], v[100:101]
	v_exp_f32_e32 v157, v106
	v_exp_f32_e32 v159, v107
	v_cvt_pk_bf16_f32 v104, v118, v124
	v_cvt_pk_bf16_f32 v105, v126, v132
	v_cvt_pk_bf16_f32 v114, v153, v155
	v_cvt_pk_bf16_f32 v115, v157, v159
	v_exp_f32_e32 v156, v102
	v_exp_f32_e32 v158, v103
	v_pk_add_f32 v[132:133], v[132:133], v[100:101]
	v_cvt_pk_bf16_f32 v106, v152, v154
	v_cvt_pk_bf16_f32 v107, v156, v158
	ds_read_b64_tr_b16 v[100:101], v188 offset:36864
	ds_read_b64_tr_b16 v[108:109], v188 offset:36896
	ds_read_b64_tr_b16 v[116:117], v188 offset:36928
	ds_read_b64_tr_b16 v[124:125], v188 offset:36960
	ds_read_b64_tr_b16 v[102:103], v188 offset:41472
	ds_read_b64_tr_b16 v[110:111], v188 offset:41504
	ds_read_b64_tr_b16 v[118:119], v188 offset:41536
	ds_read_b64_tr_b16 v[126:127], v188 offset:41568
	v_pk_add_f32 v[132:133], v[152:153], v[132:133]
	s_nop 0
	v_pk_add_f32 v[132:133], v[154:155], v[132:133]
	s_nop 0
	v_pk_add_f32 v[132:133], v[156:157], v[132:133]
	s_nop 0
	v_pk_add_f32 v[132:133], v[158:159], v[132:133]
	ds_read_b64_tr_b16 v[152:153], v188 offset:36992
	ds_read_b64_tr_b16 v[156:157], v188 offset:37024
	ds_read_b64_tr_b16 v[160:161], v188 offset:37056
	ds_read_b64_tr_b16 v[164:165], v188 offset:37088
	ds_read_b64_tr_b16 v[154:155], v188 offset:41600
	ds_read_b64_tr_b16 v[158:159], v188 offset:41632
	ds_read_b64_tr_b16 v[162:163], v188 offset:41664
	ds_read_b64_tr_b16 v[166:167], v188 offset:41696
	s_setprio 1
	s_waitcnt lgkmcnt(11)
	v_mfma_f32_16x16x32_bf16 v[60:63], v[100:103], v[128:131], v[60:63]
	v_mfma_f32_16x16x32_bf16 v[56:59], v[100:103], v[120:123], v[56:59]
	s_waitcnt lgkmcnt(10)
	v_mfma_f32_16x16x32_bf16 v[52:55], v[108:111], v[128:131], v[52:55]
	v_mfma_f32_16x16x32_bf16 v[48:51], v[108:111], v[120:123], v[48:51]
	s_waitcnt lgkmcnt(9)
	v_mfma_f32_16x16x32_bf16 v[44:47], v[116:119], v[128:131], v[44:47]
	v_mfma_f32_16x16x32_bf16 v[36:39], v[116:119], v[120:123], v[36:39]
	s_waitcnt lgkmcnt(8)
	v_mfma_f32_16x16x32_bf16 v[40:43], v[124:127], v[128:131], v[40:43]
	v_mfma_f32_16x16x32_bf16 v[24:27], v[124:127], v[120:123], v[24:27]
	s_setprio 0
	ds_read_b64_tr_b16 v[100:101], v188 offset:46080
	ds_read_b64_tr_b16 v[108:109], v188 offset:46112
	ds_read_b64_tr_b16 v[116:117], v188 offset:46144
	ds_read_b64_tr_b16 v[124:125], v188 offset:46176
	ds_read_b64_tr_b16 v[102:103], v188 offset:50688
	ds_read_b64_tr_b16 v[110:111], v188 offset:50720
	ds_read_b64_tr_b16 v[118:119], v188 offset:50752
	ds_read_b64_tr_b16 v[126:127], v188 offset:50784
	s_setprio 1
	s_waitcnt lgkmcnt(11)
	v_mfma_f32_16x16x32_bf16 v[32:35], v[152:155], v[128:131], v[32:35]
	v_mfma_f32_16x16x32_bf16 v[20:23], v[152:155], v[120:123], v[20:23]
	s_waitcnt lgkmcnt(10)
	v_mfma_f32_16x16x32_bf16 v[28:31], v[156:159], v[128:131], v[28:31]
	v_mfma_f32_16x16x32_bf16 v[8:11], v[156:159], v[120:123], v[8:11]
	s_waitcnt lgkmcnt(9)
	v_mfma_f32_16x16x32_bf16 v[4:7], v[160:163], v[128:131], v[4:7]
	v_mfma_f32_16x16x32_bf16 v[0:3], v[160:163], v[120:123], v[0:3]
	s_waitcnt lgkmcnt(8)
	v_mfma_f32_16x16x32_bf16 v[16:19], v[164:167], v[128:131], v[16:19]
	v_mfma_f32_16x16x32_bf16 v[12:15], v[164:167], v[120:123], v[12:15]
	s_setprio 0
	ds_read_b64_tr_b16 v[152:153], v188 offset:46208
	ds_read_b64_tr_b16 v[156:157], v188 offset:46240
	ds_read_b64_tr_b16 v[160:161], v188 offset:46272
	ds_read_b64_tr_b16 v[164:165], v188 offset:46304
	ds_read_b64_tr_b16 v[154:155], v188 offset:50816
	ds_read_b64_tr_b16 v[158:159], v188 offset:50848
	ds_read_b64_tr_b16 v[162:163], v188 offset:50880
	ds_read_b64_tr_b16 v[166:167], v188 offset:50912
	s_setprio 1
	s_waitcnt lgkmcnt(11)
	v_mfma_f32_16x16x32_bf16 v[60:63], v[100:103], v[112:115], v[60:63]
	v_mfma_f32_16x16x32_bf16 v[56:59], v[100:103], v[104:107], v[56:59]
	s_waitcnt lgkmcnt(10)
	v_mfma_f32_16x16x32_bf16 v[52:55], v[108:111], v[112:115], v[52:55]
	v_mfma_f32_16x16x32_bf16 v[48:51], v[108:111], v[104:107], v[48:51]
	s_waitcnt lgkmcnt(9)
	v_mfma_f32_16x16x32_bf16 v[44:47], v[116:119], v[112:115], v[44:47]
	v_mfma_f32_16x16x32_bf16 v[36:39], v[116:119], v[104:107], v[36:39]
	s_waitcnt lgkmcnt(8)
	v_mfma_f32_16x16x32_bf16 v[40:43], v[124:127], v[112:115], v[40:43]
	v_mfma_f32_16x16x32_bf16 v[24:27], v[124:127], v[104:107], v[24:27]
	s_setprio 0
	s_setprio 1
	s_waitcnt lgkmcnt(3)
	v_mfma_f32_16x16x32_bf16 v[32:35], v[152:155], v[112:115], v[32:35]
	v_mfma_f32_16x16x32_bf16 v[20:23], v[152:155], v[104:107], v[20:23]
	s_waitcnt lgkmcnt(2)
	v_mfma_f32_16x16x32_bf16 v[28:31], v[156:159], v[112:115], v[28:31]
	v_mfma_f32_16x16x32_bf16 v[8:11], v[156:159], v[104:107], v[8:11]
	s_waitcnt lgkmcnt(1)
	v_mfma_f32_16x16x32_bf16 v[4:7], v[160:163], v[112:115], v[4:7]
	v_mfma_f32_16x16x32_bf16 v[0:3], v[160:163], v[104:107], v[0:3]
	s_waitcnt lgkmcnt(0)
	v_mfma_f32_16x16x32_bf16 v[16:19], v[164:167], v[112:115], v[16:19]
	v_mfma_f32_16x16x32_bf16 v[12:15], v[164:167], v[104:107], v[12:15]
	s_setprio 0
; #define AT_STORE(buf) do { _Pragma("unroll") for (int j = 0; j < 2; ++j) { const int c = tid + 512 * j; \
;         *(LAS u32x4*)(lds + AT_K + (buf) * AT_KBUF + (c >> 4) * AT_KROW + (c & 15) * 16) = rk[j]; \
;         *(LAS u32x4*)(lds + AT_V + (buf) * AT_VBUF + (c >> 4) * AT_VROW + (c & 15) * 16) = rv[j]; } } while (0)
; __device__ __forceinline__ void attn_unit(LAS unsigned char* lds, const bf16* UA, bf16* Y, int bl, int h, int qb,
;                                           const float* qkg, const float* rel_bias, const float* lamv, const float* dgain, float lam_init, int tid, int wave, int lane) {
;     ...
;         if (kt + 1 < NT) AT_STORE(buf ^ 1);
;         __syncthreads();
.LBB0_524:
	s_xor_b32 s24, s43, 1
	s_mulk_i32 s24, 0x4800
	v_add_u32_e32 v100, s24, v148
	v_add_u32_e32 v101, v100, v147
	s_add_i32 s42, s42, -1
	s_addk_i32 s37, 0x100
	s_add_i32 s11, s11, 1
	s_waitcnt vmcnt(7)
	ds_write_b128 v101, v[232:235]
	s_waitcnt vmcnt(6)
	ds_write_b128 v101, v[236:239] offset:36864
	v_add_u32_e32 v102, v100, v149
	v_lshl_add_u64 v[134:135], v[134:135], 0, s[52:53]
	s_cmp_eq_u32 s36, s37
	v_lshl_add_u64 v[136:137], v[136:137], 0, s[52:53]
	s_waitcnt vmcnt(5)
	ds_write_b128 v102, v[240:243]
	s_waitcnt vmcnt(4)
	ds_write_b128 v102, v[244:247] offset:36864
	s_waitcnt lgkmcnt(0)
	s_barrier
	s_cbranch_scc1 .Latt_exit
	s_branch .Latt_o_top

; #define AT_STORE(buf) do { _Pragma("unroll") for (int j = 0; j < 2; ++j) { const int c = tid + 512 * j; \
;         *(LAS u32x4*)(lds + AT_K + (buf) * AT_KBUF + (c >> 4) * AT_KROW + (c & 15) * 16) = rk[j]; \
;         *(LAS u32x4*)(lds + AT_V + (buf) * AT_VBUF + (c >> 4) * AT_VROW + (c & 15) * 16) = rv[j]; } } while (0)
; __device__ __forceinline__ void attn_unit(LAS unsigned char* lds, const bf16* UA, bf16* Y, int bl, int h, int qb,
;                                           const float* qkg, const float* rel_bias, const float* lamv, const float* dgain, float lam_init, int tid, int wave, int lane) {
;     ...
;         if (kt + 1 < NT) AT_STORE(buf ^ 1);
;         __syncthreads();
;     }
.Latt_exit:
	s_waitcnt vmcnt(0)
	s_branch .LBB0_539

; #define LAS __attribute__((address_space(3)))
; #define AT_LOAD(kt) do { _Pragma("unroll") for (int j = 0; j < 2; ++j) { const int c = tid + 512 * j; \
;         rk[j] = *(const u32x4*)(ksrc + (size_t)((kt) * 64 + (c >> 4)) * 3072 + (c & 15) * 8); \
;         rv[j] = *(const u32x4*)(vsrc + (size_t)((kt) * 64 + (c >> 4)) * 3072 + (c & 15) * 8); } } while (0)
; __device__ __forceinline__ void attn_unit(LAS unsigned char* lds, const bf16* UA, bf16* Y, int bl, int h, int qb,
;                                           const float* qkg, const float* rel_bias, const float* lamv, const float* dgain, float lam_init, int tid, int wave, int lane) {
;     ...
;         if (kt + 1 < NT) AT_LOAD(kt + 1);
;         if (kt <= qc) {
;             const bool far_ = (qc - kt) >= 3;
;             const LAS unsigned char* Kb = lds + AT_K + buf * AT_KBUF;
;             const LAS unsigned char* Vb = lds + AT_V + buf * AT_VBUF;
;             f32x4 S[4][2];
;             bf16x8 kf[4][2];
; #pragma unroll
;             for (int kb = 0; kb < 4; ++kb)
; #pragma unroll
;                 for (int ks = 0; ks < 2; ++ks) kf[kb][ks] = *(const LAS bf16x8*)(Kb + koff + (16 * kb) * AT_KROW + ks * 64);
;             __builtin_amdgcn_s_setprio(1);
; #pragma unroll
;             for (int kb = 0; kb < 4; ++kb)
; #pragma unroll
;                 for (int qb2 = 0; qb2 < 2; ++qb2) S[kb][qb2] = __builtin_amdgcn_mfma_f32_16x16x32_bf16(kf[kb][0], qr[qb2][0], CI, 0, 0, 0);
; #pragma unroll
;             for (int kb = 0; kb < 4; ++kb)
; #pragma unroll
;                 for (int qb2 = 0; qb2 < 2; ++qb2) S[kb][qb2] = __builtin_amdgcn_mfma_f32_16x16x32_bf16(kf[kb][1], qr[qb2][1], S[kb][qb2], 0, 0, 0);
;             __builtin_amdgcn_s_setprio(0);
;             if (!far_) {
;                 const int rbase = 64 * kt - (q0 + x) + 191 + 4 * g;
; #pragma unroll
;                 for (int kb = 0; kb < 4; ++kb)
; #pragma unroll
;                     for (int qb2 = 0; qb2 < 2; ++qb2)
; #pragma unroll
;                         for (int i = 0; i < 4; ++i) S[kb][qb2][i] += tbl[rbase + 16 * kb - 16 * qb2 + i];
.Latt_o_e:
	s_xor_b32 s24, s43, 1
	s_mulk_i32 s24, 0x4800
	v_add_u32_e32 v100, s24, v148
	v_add_u32_e32 v101, v100, v147
	s_add_i32 s42, s42, -1
	s_addk_i32 s37, 0x100
	s_add_i32 s11, s11, 1
	s_waitcnt vmcnt(7)
	ds_write_b128 v101, v[84:87]
	s_waitcnt vmcnt(6)
	ds_write_b128 v101, v[88:91] offset:36864
	v_add_u32_e32 v102, v100, v149
	v_lshl_add_u64 v[134:135], v[134:135], 0, s[52:53]
	s_cmp_eq_u32 s36, s37
	v_lshl_add_u64 v[136:137], v[136:137], 0, s[52:53]
	s_waitcnt vmcnt(5)
	ds_write_b128 v102, v[92:95]
	s_waitcnt vmcnt(4)
	ds_write_b128 v102, v[96:99] offset:36864
	s_waitcnt lgkmcnt(0)
	s_barrier
	s_cbranch_scc1 .Latt_exit
	s_branch .LBB0_525
.Latt_o_top:
	v_lshl_add_u64 v[232:233], v[134:135], 0, s[12:13]
	s_mov_b32 s24, 0x23860000
	v_add_co_u32_e32 v234, vcc, s24, v232
	v_lshl_add_u64 v[240:241], v[136:137], 0, s[12:13]
	s_nop 0
	v_addc_co_u32_e32 v235, vcc, 0, v233, vcc
	v_add_co_u32_e32 v236, vcc, 0x23861000, v232
	s_and_b32 s43, s11, 1
	s_nop 0
	v_addc_co_u32_e32 v237, vcc, 0, v233, vcc
	v_add_co_u32_e32 v242, vcc, 0x23860000, v240
	global_load_dwordx4 v[232:235], v[234:235], off offset:2048
	s_nop 0
	global_load_dwordx4 v[236:239], v[236:237], off
	v_addc_co_u32_e32 v243, vcc, 0, v241, vcc
	v_add_co_u32_e32 v244, vcc, 0x23861000, v240
	s_cmp_gt_u32 s11, s27
	s_nop 0
	v_addc_co_u32_e32 v245, vcc, 0, v241, vcc
	global_load_dwordx4 v[240:243], v[242:243], off offset:2048
	s_nop 0
	global_load_dwordx4 v[244:247], v[244:245], off
	s_cbranch_scc1 .Latt_o_e
	s_mul_i32 s44, s43, 0x4800
	v_add_u32_e32 v124, s44, v150
	ds_read_b128 v[100:103], v124
	ds_read_b128 v[104:107], v124 offset:64
	ds_read_b128 v[108:111], v124 offset:4608
	ds_read_b128 v[112:115], v124 offset:4672
	ds_read_b128 v[116:119], v124 offset:9216
	ds_read_b128 v[152:155], v124 offset:9280
	ds_read_b128 v[120:123], v124 offset:13824
	ds_read_b128 v[156:159], v124 offset:13888
	s_setprio 1
	s_waitcnt lgkmcnt(7)
	v_mfma_f32_16x16x32_bf16 v[124:127], v[100:103], v[72:75], v[64:67]
	s_cmp_gt_u32 s42, 2
	v_mfma_f32_16x16x32_bf16 v[100:103], v[100:103], v[80:83], v[64:67]
	s_waitcnt lgkmcnt(5)
	v_mfma_f32_16x16x32_bf16 v[160:163], v[108:111], v[72:75], v[64:67]
	v_mfma_f32_16x16x32_bf16 v[108:111], v[108:111], v[80:83], v[64:67]
	s_waitcnt lgkmcnt(3)
	v_mfma_f32_16x16x32_bf16 v[164:167], v[116:119], v[72:75], v[64:67]
	v_mfma_f32_16x16x32_bf16 v[188:191], v[116:119], v[80:83], v[64:67]
	s_waitcnt lgkmcnt(1)
	v_mfma_f32_16x16x32_bf16 v[192:195], v[120:123], v[72:75], v[64:67]
	v_mfma_f32_16x16x32_bf16 v[196:199], v[120:123], v[80:83], v[64:67]
	v_mfma_f32_16x16x32_bf16 v[128:131], v[104:107], v[68:71], v[124:127]
	v_mfma_f32_16x16x32_bf16 v[124:127], v[104:107], v[76:79], v[100:103]
	v_mfma_f32_16x16x32_bf16 v[120:123], v[112:115], v[68:71], v[160:163]
	v_mfma_f32_16x16x32_bf16 v[116:119], v[112:115], v[76:79], v[108:111]
	v_mfma_f32_16x16x32_bf16 v[112:115], v[152:155], v[68:71], v[164:167]
	v_mfma_f32_16x16x32_bf16 v[108:111], v[152:155], v[76:79], v[188:191]
	s_waitcnt lgkmcnt(0)
	v_mfma_f32_16x16x32_bf16 v[104:107], v[156:159], v[68:71], v[192:195]
	v_mfma_f32_16x16x32_bf16 v[100:103], v[156:159], v[76:79], v[196:199]
	s_setprio 0
	s_cbranch_scc1 .Latt_o_cd
	v_add_u32_e32 v156, s37, v151
	v_add_u32_e32 v152, 0x123bc, v156
	v_add_u32_e32 v154, 0x123c4, v156
	ds_read2_b32 v[152:153], v152 offset1:1
	ds_read2_b32 v[154:155], v154 offset1:1
	v_add_u32_e32 v157, 0x123fc, v156
	v_add_u32_e32 v158, 0x12404, v156
	v_add_u32_e32 v159, 0x1243c, v156
	s_waitcnt lgkmcnt(1)
	v_pk_add_f32 v[124:125], v[124:125], v[152:153]
	s_waitcnt lgkmcnt(0)
	v_pk_add_f32 v[126:127], v[126:127], v[154:155]
	ds_read2_b32 v[152:153], v157 offset1:1
	ds_read2_b32 v[154:155], v158 offset1:1
	v_add_u32_e32 v160, 0x12444, v156
	v_add_u32_e32 v157, 0x1247c, v156
	v_add_u32_e32 v158, 0x12484, v156
	s_waitcnt lgkmcnt(1)
	v_pk_add_f32 v[128:129], v[128:129], v[152:153]
	s_waitcnt lgkmcnt(0)
	v_pk_add_f32 v[130:131], v[130:131], v[154:155]
	v_pk_add_f32 v[118:119], v[118:119], v[154:155]
	v_pk_add_f32 v[116:117], v[116:117], v[152:153]
	ds_read2_b32 v[152:153], v159 offset1:1
	ds_read2_b32 v[154:155], v160 offset1:1
	s_waitcnt lgkmcnt(1)
	v_pk_add_f32 v[120:121], v[120:121], v[152:153]
	s_waitcnt lgkmcnt(0)
	v_pk_add_f32 v[122:123], v[122:123], v[154:155]
	v_pk_add_f32 v[110:111], v[110:111], v[154:155]
	v_pk_add_f32 v[108:109], v[108:109], v[152:153]
	v_add_u32_e32 v152, 0x124bc, v156
	v_add_u32_e32 v154, 0x124c4, v156
	ds_read2_b32 v[152:153], v152 offset1:1
	ds_read2_b32 v[154:155], v154 offset1:1
	s_waitcnt lgkmcnt(1)
	v_pk_add_f32 v[104:105], v[104:105], v[152:153]
	s_waitcnt lgkmcnt(0)
	v_pk_add_f32 v[106:107], v[106:107], v[154:155]
	ds_read2_b32 v[152:153], v157 offset1:1
	ds_read2_b32 v[154:155], v158 offset1:1
	s_waitcnt lgkmcnt(1)
	v_pk_add_f32 v[112:113], v[112:113], v[152:153]
	s_waitcnt lgkmcnt(0)
	v_pk_add_f32 v[114:115], v[114:115], v[154:155]
	v_pk_add_f32 v[102:103], v[102:103], v[154:155]
	v_pk_add_f32 v[100:101], v[100:101], v[152:153]
	s_branch .Latt_o_cd

; __device__ __forceinline__ unsigned cvt_pk_bf16(float lo, float hi) { unsigned r; asm volatile("v_cvt_pk_bf16_f32 %0, %1, %2" : "=v"(r) : "v"(lo), "v"(hi)); return r; }
; #define PG8_BAR __builtin_amdgcn_s_barrier()
; template <class Epi>
; __device__ __forceinline__ void gemm_phase(LAS unsigned char* lds, const Gemm g, const StaticOrder& S, const Epi& E, const int tid) {
;     ...
;         if (wr == 0) PG8_BAR;
;     __device__ __forceinline__ void operator()(f32x4 (&acc)[2][2][4][2], const Unit& u, int wr, int wc, int fr, int fq) const {
;         const int row0 = u.pm * BM + wr * 64 + fr, col0 = u.pn * 128 + wc * 32 + 8 * fq;
; #pragma unroll
;         for (int ai = 0; ai < 2; ++ai)
; #pragma unroll
;             for (int m = 0; m < 4; ++m) {
;                 bf16* rowp = O + (size_t)(row0 + ai * HALF + m * 16) * FF + col0;
;                 const f32x4 g0 = acc[ai][0][m][0], g1 = acc[ai][0][m][1], u0 = acc[ai][1][m][0], u1 = acc[ai][1][m][1];
;                 u32x4 w;
;                 const f32x4 a0 = swiglu4(g0, u0), a1 = swiglu4(g1, u1);
;                 w.x = cvt_pk_bf16(a0[0], a0[1]); w.y = cvt_pk_bf16(a0[2], a0[3]); w.z = cvt_pk_bf16(a1[0], a1[1]); w.w = cvt_pk_bf16(a1[2], a1[3]);
;                 __builtin_nontemporal_store(w, (u32x4*)rowp);
;             }
.LBB0_1007:
	v_pk_mul_f32 v[150:151], v[126:127], s[74:75] op_sel_hi:[1,0]
	v_pk_mul_f32 v[152:153], v[124:125], s[74:75] op_sel_hi:[1,0]
	v_pk_mul_f32 v[122:123], v[126:127], v[122:123]
	v_pk_mul_f32 v[120:121], v[124:125], v[120:121]
	v_pk_mul_f32 v[124:125], v[118:119], s[74:75] op_sel_hi:[1,0]
	v_pk_mul_f32 v[126:127], v[116:117], s[74:75] op_sel_hi:[1,0]
	v_exp_f32_e32 v124, v124
	v_exp_f32_e32 v126, v126
	v_exp_f32_e32 v125, v125
	v_exp_f32_e32 v127, v127
	v_exp_f32_e32 v152, v152
	v_exp_f32_e32 v150, v150
	v_exp_f32_e32 v151, v151
	v_exp_f32_e32 v153, v153
	v_pk_add_f32 v[124:125], v[124:125], 1.0 op_sel_hi:[1,0]
	v_pk_add_f32 v[126:127], v[126:127], 1.0 op_sel_hi:[1,0]
	v_pk_add_f32 v[150:151], v[150:151], 1.0 op_sel_hi:[1,0]
	v_pk_add_f32 v[152:153], v[152:153], 1.0 op_sel_hi:[1,0]
	v_rcp_f32_e32 v126, v126
	v_rcp_f32_e32 v124, v124
	v_rcp_f32_e32 v125, v125
	v_rcp_f32_e32 v127, v127
	v_readlane_b32 s0, v254, 23
	v_rcp_f32_e32 v152, v152
	v_rcp_f32_e32 v153, v153
	v_rcp_f32_e32 v150, v150
	v_rcp_f32_e32 v151, v151
	v_lshl_or_b32 v140, s47, 7, v144
	v_readlane_b32 s1, v254, 24
	v_lshl_add_u32 v146, s48, 8, v142
	v_ashrrev_i32_e32 v141, 31, v140
	v_mov_b64_e32 v[138:139], s[0:1]
	s_movk_i32 s2, 0x2c00
	v_pk_mul_f32 v[114:115], v[118:119], v[114:115]
	v_pk_mul_f32 v[112:113], v[116:117], v[112:113]
	v_mad_i64_i32 v[148:149], s[0:1], v146, s2, v[138:139]
	v_lshlrev_b64 v[140:141], 1, v[140:141]
	v_pk_mul_f32 v[116:117], v[124:125], v[114:115]
	v_pk_mul_f32 v[114:115], v[126:127], v[112:113]
	v_lshl_add_u64 v[148:149], v[148:149], 0, v[140:141]
	v_pk_mul_f32 v[122:123], v[150:151], v[122:123]
	v_pk_mul_f32 v[120:121], v[152:153], v[120:121]
	v_pk_mul_f32 v[106:107], v[110:111], v[106:107]
	v_cvt_pk_bf16_f32 v112, v120, v121
	v_cvt_pk_bf16_f32 v113, v122, v123
	v_cvt_pk_bf16_f32 v114, v114, v115
	v_cvt_pk_bf16_f32 v115, v116, v117
	global_store_dwordx4 v[148:149], v[112:115], off nt
	v_pk_mul_f32 v[104:105], v[108:109], v[104:105]
	v_or_b32_e32 v116, 16, v146
	v_pk_mul_f32 v[112:113], v[110:111], s[74:75] op_sel_hi:[1,0]
	v_pk_mul_f32 v[114:115], v[108:109], s[74:75] op_sel_hi:[1,0]
	v_pk_mul_f32 v[108:109], v[102:103], s[74:75] op_sel_hi:[1,0]
	v_pk_mul_f32 v[110:111], v[100:101], s[74:75] op_sel_hi:[1,0]
	v_exp_f32_e32 v108, v108
	v_exp_f32_e32 v110, v110
	v_exp_f32_e32 v109, v109
	v_exp_f32_e32 v111, v111
	v_exp_f32_e32 v114, v114
	v_exp_f32_e32 v115, v115
	v_exp_f32_e32 v112, v112
	v_exp_f32_e32 v113, v113
	v_pk_add_f32 v[108:109], v[108:109], 1.0 op_sel_hi:[1,0]
	v_pk_add_f32 v[110:111], v[110:111], 1.0 op_sel_hi:[1,0]
	v_pk_add_f32 v[114:115], v[114:115], 1.0 op_sel_hi:[1,0]
	v_pk_add_f32 v[112:113], v[112:113], 1.0 op_sel_hi:[1,0]
	v_rcp_f32_e32 v110, v110
	v_rcp_f32_e32 v108, v108
	v_rcp_f32_e32 v109, v109
	v_rcp_f32_e32 v111, v111
	v_rcp_f32_e32 v114, v114
	v_rcp_f32_e32 v115, v115
	v_rcp_f32_e32 v112, v112
	v_rcp_f32_e32 v113, v113
	v_pk_mul_f32 v[98:99], v[102:103], v[98:99]
	v_pk_mul_f32 v[96:97], v[100:101], v[96:97]
	v_mad_i64_i32 v[116:117], s[0:1], v116, s2, v[138:139]
	v_pk_mul_f32 v[100:101], v[108:109], v[98:99]
	v_pk_mul_f32 v[98:99], v[110:111], v[96:97]
	v_lshl_add_u64 v[116:117], v[116:117], 0, v[140:141]
	v_pk_mul_f32 v[106:107], v[112:113], v[106:107]
	v_pk_mul_f32 v[104:105], v[114:115], v[104:105]
	v_pk_mul_f32 v[90:91], v[94:95], v[90:91]
	v_cvt_pk_bf16_f32 v96, v104, v105
	v_cvt_pk_bf16_f32 v97, v106, v107
	v_cvt_pk_bf16_f32 v98, v98, v99
	v_cvt_pk_bf16_f32 v99, v100, v101
	global_store_dwordx4 v[116:117], v[96:99], off nt
	v_pk_mul_f32 v[88:89], v[92:93], v[88:89]
	v_or_b32_e32 v100, 32, v146
	v_pk_mul_f32 v[96:97], v[94:95], s[74:75] op_sel_hi:[1,0]
	v_pk_mul_f32 v[98:99], v[92:93], s[74:75] op_sel_hi:[1,0]
	v_pk_mul_f32 v[92:93], v[86:87], s[74:75] op_sel_hi:[1,0]
	v_pk_mul_f32 v[94:95], v[84:85], s[74:75] op_sel_hi:[1,0]
	v_exp_f32_e32 v92, v92
	v_exp_f32_e32 v94, v94
	v_exp_f32_e32 v93, v93
	v_exp_f32_e32 v95, v95
	v_exp_f32_e32 v98, v98
	v_exp_f32_e32 v99, v99
	v_exp_f32_e32 v96, v96
	v_exp_f32_e32 v97, v97
	v_pk_add_f32 v[92:93], v[92:93], 1.0 op_sel_hi:[1,0]
	v_pk_add_f32 v[94:95], v[94:95], 1.0 op_sel_hi:[1,0]
	v_pk_add_f32 v[98:99], v[98:99], 1.0 op_sel_hi:[1,0]
	v_pk_add_f32 v[96:97], v[96:97], 1.0 op_sel_hi:[1,0]
	v_rcp_f32_e32 v94, v94
	v_rcp_f32_e32 v92, v92
	v_rcp_f32_e32 v93, v93
	v_rcp_f32_e32 v95, v95
	v_rcp_f32_e32 v98, v98
	v_rcp_f32_e32 v99, v99
	v_rcp_f32_e32 v96, v96
	v_rcp_f32_e32 v97, v97
	v_pk_mul_f32 v[82:83], v[86:87], v[82:83]
	v_pk_mul_f32 v[80:81], v[84:85], v[80:81]
	v_mad_i64_i32 v[100:101], s[0:1], v100, s2, v[138:139]
	v_pk_mul_f32 v[84:85], v[92:93], v[82:83]
	v_pk_mul_f32 v[82:83], v[94:95], v[80:81]
	v_lshl_add_u64 v[100:101], v[100:101], 0, v[140:141]
	v_pk_mul_f32 v[90:91], v[96:97], v[90:91]
	v_pk_mul_f32 v[88:89], v[98:99], v[88:89]
	v_pk_mul_f32 v[74:75], v[78:79], v[74:75]
	v_cvt_pk_bf16_f32 v80, v88, v89
	v_cvt_pk_bf16_f32 v81, v90, v91
	v_cvt_pk_bf16_f32 v82, v82, v83
	v_cvt_pk_bf16_f32 v83, v84, v85
	global_store_dwordx4 v[100:101], v[80:83], off nt
	v_pk_mul_f32 v[72:73], v[76:77], v[72:73]
	v_or_b32_e32 v84, 48, v146
	v_pk_mul_f32 v[80:81], v[78:79], s[74:75] op_sel_hi:[1,0]
	v_pk_mul_f32 v[82:83], v[76:77], s[74:75] op_sel_hi:[1,0]
	v_pk_mul_f32 v[76:77], v[70:71], s[74:75] op_sel_hi:[1,0]
	v_pk_mul_f32 v[78:79], v[68:69], s[74:75] op_sel_hi:[1,0]
	v_exp_f32_e32 v76, v76
	v_exp_f32_e32 v78, v78
	v_exp_f32_e32 v77, v77
	v_exp_f32_e32 v79, v79
	v_exp_f32_e32 v82, v82
	v_exp_f32_e32 v83, v83
	v_exp_f32_e32 v80, v80
	v_exp_f32_e32 v81, v81
	v_pk_add_f32 v[76:77], v[76:77], 1.0 op_sel_hi:[1,0]
	v_pk_add_f32 v[78:79], v[78:79], 1.0 op_sel_hi:[1,0]
; __device__ __forceinline__ unsigned cvt_pk_bf16(float lo, float hi) { unsigned r; asm volatile("v_cvt_pk_bf16_f32 %0, %1, %2" : "=v"(r) : "v"(lo), "v"(hi)); return r; }
; #define PG8_BAR __builtin_amdgcn_s_barrier()
; template <class Epi>
; __device__ __forceinline__ void gemm_phase(LAS unsigned char* lds, const Gemm g, const StaticOrder& S, const Epi& E, const int tid) {
;     ...
;         if (wr == 0) PG8_BAR;
;     __device__ __forceinline__ void operator()(f32x4 (&acc)[2][2][4][2], const Unit& u, int wr, int wc, int fr, int fq) const {
;     ...
;             for (int m = 0; m < 4; ++m) {
;                 bf16* rowp = O + (size_t)(row0 + ai * HALF + m * 16) * FF + col0;
;                 const f32x4 g0 = acc[ai][0][m][0], g1 = acc[ai][0][m][1], u0 = acc[ai][1][m][0], u1 = acc[ai][1][m][1];
;                 u32x4 w;
;                 const f32x4 a0 = swiglu4(g0, u0), a1 = swiglu4(g1, u1);
;                 w.x = cvt_pk_bf16(a0[0], a0[1]); w.y = cvt_pk_bf16(a0[2], a0[3]); w.z = cvt_pk_bf16(a1[0], a1[1]); w.w = cvt_pk_bf16(a1[2], a1[3]);
;                 __builtin_nontemporal_store(w, (u32x4*)rowp);
;             }
	v_pk_add_f32 v[82:83], v[82:83], 1.0 op_sel_hi:[1,0]
	v_pk_add_f32 v[80:81], v[80:81], 1.0 op_sel_hi:[1,0]
	v_rcp_f32_e32 v78, v78
	v_rcp_f32_e32 v76, v76
	v_rcp_f32_e32 v77, v77
	v_rcp_f32_e32 v79, v79
	v_rcp_f32_e32 v82, v82
	v_rcp_f32_e32 v83, v83
	v_rcp_f32_e32 v80, v80
	v_rcp_f32_e32 v81, v81
	v_pk_mul_f32 v[66:67], v[70:71], v[66:67]
	v_pk_mul_f32 v[64:65], v[68:69], v[64:65]
	v_mad_i64_i32 v[84:85], s[0:1], v84, s2, v[138:139]
	v_pk_mul_f32 v[68:69], v[76:77], v[66:67]
	v_pk_mul_f32 v[66:67], v[78:79], v[64:65]
	v_lshl_add_u64 v[84:85], v[84:85], 0, v[140:141]
	v_pk_mul_f32 v[74:75], v[80:81], v[74:75]
	v_pk_mul_f32 v[72:73], v[82:83], v[72:73]
	v_pk_mul_f32 v[58:59], v[62:63], v[58:59]
	v_cvt_pk_bf16_f32 v64, v72, v73
	v_cvt_pk_bf16_f32 v65, v74, v75
	v_cvt_pk_bf16_f32 v66, v66, v67
	v_cvt_pk_bf16_f32 v67, v68, v69
	global_store_dwordx4 v[84:85], v[64:67], off nt
	v_pk_mul_f32 v[56:57], v[60:61], v[56:57]
	v_add_u32_e32 v68, 0x80, v146
	v_pk_mul_f32 v[64:65], v[62:63], s[74:75] op_sel_hi:[1,0]
	v_pk_mul_f32 v[66:67], v[60:61], s[74:75] op_sel_hi:[1,0]
	v_pk_mul_f32 v[60:61], v[54:55], s[74:75] op_sel_hi:[1,0]
	v_pk_mul_f32 v[62:63], v[52:53], s[74:75] op_sel_hi:[1,0]
	v_exp_f32_e32 v60, v60
	v_exp_f32_e32 v62, v62
	v_exp_f32_e32 v61, v61
	v_exp_f32_e32 v63, v63
	v_exp_f32_e32 v66, v66
	v_exp_f32_e32 v67, v67
	v_exp_f32_e32 v64, v64
	v_exp_f32_e32 v65, v65
	v_pk_add_f32 v[60:61], v[60:61], 1.0 op_sel_hi:[1,0]
	v_pk_add_f32 v[62:63], v[62:63], 1.0 op_sel_hi:[1,0]
	v_pk_add_f32 v[66:67], v[66:67], 1.0 op_sel_hi:[1,0]
	v_pk_add_f32 v[64:65], v[64:65], 1.0 op_sel_hi:[1,0]
	v_rcp_f32_e32 v62, v62
	v_rcp_f32_e32 v60, v60
	v_rcp_f32_e32 v61, v61
	v_rcp_f32_e32 v63, v63
	v_rcp_f32_e32 v66, v66
	v_rcp_f32_e32 v67, v67
	v_rcp_f32_e32 v64, v64
	v_rcp_f32_e32 v65, v65
	v_pk_mul_f32 v[50:51], v[54:55], v[50:51]
	v_pk_mul_f32 v[48:49], v[52:53], v[48:49]
	v_mad_i64_i32 v[68:69], s[0:1], v68, s2, v[138:139]
	v_pk_mul_f32 v[52:53], v[60:61], v[50:51]
	v_pk_mul_f32 v[50:51], v[62:63], v[48:49]
	v_lshl_add_u64 v[68:69], v[68:69], 0, v[140:141]
	v_pk_mul_f32 v[58:59], v[64:65], v[58:59]
	v_pk_mul_f32 v[56:57], v[66:67], v[56:57]
	v_pk_mul_f32 v[42:43], v[46:47], v[42:43]
	v_cvt_pk_bf16_f32 v48, v56, v57
	v_cvt_pk_bf16_f32 v49, v58, v59
	v_cvt_pk_bf16_f32 v50, v50, v51
	v_cvt_pk_bf16_f32 v51, v52, v53
	global_store_dwordx4 v[68:69], v[48:51], off nt
	v_pk_mul_f32 v[40:41], v[44:45], v[40:41]
	v_add_u32_e32 v52, 0x90, v146
	v_pk_mul_f32 v[48:49], v[46:47], s[74:75] op_sel_hi:[1,0]
	v_pk_mul_f32 v[50:51], v[44:45], s[74:75] op_sel_hi:[1,0]
	v_pk_mul_f32 v[44:45], v[38:39], s[74:75] op_sel_hi:[1,0]
	v_pk_mul_f32 v[46:47], v[36:37], s[74:75] op_sel_hi:[1,0]
	v_exp_f32_e32 v44, v44
	v_exp_f32_e32 v46, v46
	v_exp_f32_e32 v45, v45
	v_exp_f32_e32 v47, v47
	v_exp_f32_e32 v50, v50
	v_exp_f32_e32 v51, v51
	v_exp_f32_e32 v48, v48
	v_exp_f32_e32 v49, v49
	v_pk_add_f32 v[44:45], v[44:45], 1.0 op_sel_hi:[1,0]
	v_pk_add_f32 v[46:47], v[46:47], 1.0 op_sel_hi:[1,0]
	v_pk_add_f32 v[50:51], v[50:51], 1.0 op_sel_hi:[1,0]
	v_pk_add_f32 v[48:49], v[48:49], 1.0 op_sel_hi:[1,0]
	v_rcp_f32_e32 v46, v46
	v_rcp_f32_e32 v44, v44
	v_rcp_f32_e32 v45, v45
	v_rcp_f32_e32 v47, v47
	v_rcp_f32_e32 v50, v50
	v_rcp_f32_e32 v51, v51
	v_rcp_f32_e32 v48, v48
	v_rcp_f32_e32 v49, v49
	v_pk_mul_f32 v[34:35], v[38:39], v[34:35]
	v_pk_mul_f32 v[32:33], v[36:37], v[32:33]
	v_mad_i64_i32 v[52:53], s[0:1], v52, s2, v[138:139]
	v_pk_mul_f32 v[36:37], v[44:45], v[34:35]
	v_pk_mul_f32 v[34:35], v[46:47], v[32:33]
	v_lshl_add_u64 v[52:53], v[52:53], 0, v[140:141]
	v_pk_mul_f32 v[42:43], v[48:49], v[42:43]
	v_pk_mul_f32 v[40:41], v[50:51], v[40:41]
	v_pk_mul_f32 v[26:27], v[30:31], v[26:27]
	v_cvt_pk_bf16_f32 v32, v40, v41
	v_cvt_pk_bf16_f32 v33, v42, v43
	v_cvt_pk_bf16_f32 v34, v34, v35
	v_cvt_pk_bf16_f32 v35, v36, v37
	global_store_dwordx4 v[52:53], v[32:35], off nt
	v_pk_mul_f32 v[24:25], v[28:29], v[24:25]
	v_add_u32_e32 v36, 0xa0, v146
	v_pk_mul_f32 v[32:33], v[30:31], s[74:75] op_sel_hi:[1,0]
	v_pk_mul_f32 v[34:35], v[28:29], s[74:75] op_sel_hi:[1,0]
	v_pk_mul_f32 v[28:29], v[22:23], s[74:75] op_sel_hi:[1,0]
	v_pk_mul_f32 v[30:31], v[20:21], s[74:75] op_sel_hi:[1,0]
	v_exp_f32_e32 v28, v28
	v_exp_f32_e32 v30, v30
	v_exp_f32_e32 v29, v29
	v_exp_f32_e32 v31, v31
	v_exp_f32_e32 v34, v34
	v_exp_f32_e32 v35, v35
	v_exp_f32_e32 v32, v32
	v_exp_f32_e32 v33, v33
	v_pk_add_f32 v[28:29], v[28:29], 1.0 op_sel_hi:[1,0]
	v_pk_add_f32 v[30:31], v[30:31], 1.0 op_sel_hi:[1,0]
	v_pk_add_f32 v[34:35], v[34:35], 1.0 op_sel_hi:[1,0]
	v_pk_add_f32 v[32:33], v[32:33], 1.0 op_sel_hi:[1,0]
	v_rcp_f32_e32 v30, v30
	v_rcp_f32_e32 v28, v28
	v_rcp_f32_e32 v29, v29
	v_rcp_f32_e32 v31, v31
	v_rcp_f32_e32 v34, v34
	v_rcp_f32_e32 v35, v35
	v_rcp_f32_e32 v32, v32
	v_rcp_f32_e32 v33, v33
	v_pk_mul_f32 v[18:19], v[22:23], v[18:19]
	v_pk_mul_f32 v[16:17], v[20:21], v[16:17]
	v_mad_i64_i32 v[36:37], s[0:1], v36, s2, v[138:139]
	v_pk_mul_f32 v[20:21], v[28:29], v[18:19]
	v_pk_mul_f32 v[18:19], v[30:31], v[16:17]
	v_lshl_add_u64 v[36:37], v[36:37], 0, v[140:141]
	v_pk_mul_f32 v[26:27], v[32:33], v[26:27]
	v_pk_mul_f32 v[24:25], v[34:35], v[24:25]
	v_pk_mul_f32 v[10:11], v[14:15], v[10:11]
	v_cvt_pk_bf16_f32 v16, v24, v25
	v_cvt_pk_bf16_f32 v17, v26, v27
	v_cvt_pk_bf16_f32 v18, v18, v19
	v_cvt_pk_bf16_f32 v19, v20, v21
	global_store_dwordx4 v[36:37], v[16:19], off nt
	v_pk_mul_f32 v[8:9], v[12:13], v[8:9]
	v_add_u32_e32 v20, 0xb0, v146
	v_pk_mul_f32 v[16:17], v[14:15], s[74:75] op_sel_hi:[1,0]
	v_pk_mul_f32 v[18:19], v[12:13], s[74:75] op_sel_hi:[1,0]
	v_pk_mul_f32 v[12:13], v[6:7], s[74:75] op_sel_hi:[1,0]
	v_pk_mul_f32 v[14:15], v[4:5], s[74:75] op_sel_hi:[1,0]
	v_exp_f32_e32 v12, v12
	v_exp_f32_e32 v14, v14
	v_exp_f32_e32 v13, v13
	v_exp_f32_e32 v15, v15
	v_exp_f32_e32 v18, v18
	v_exp_f32_e32 v19, v19
	v_exp_f32_e32 v16, v16
	v_exp_f32_e32 v17, v17
	v_pk_add_f32 v[12:13], v[12:13], 1.0 op_sel_hi:[1,0]
	v_pk_add_f32 v[14:15], v[14:15], 1.0 op_sel_hi:[1,0]
	v_pk_add_f32 v[18:19], v[18:19], 1.0 op_sel_hi:[1,0]
	v_pk_add_f32 v[16:17], v[16:17], 1.0 op_sel_hi:[1,0]
	v_rcp_f32_e32 v14, v14
	v_rcp_f32_e32 v12, v12
	v_rcp_f32_e32 v13, v13
	v_rcp_f32_e32 v15, v15
	v_rcp_f32_e32 v18, v18
	v_rcp_f32_e32 v19, v19
	v_rcp_f32_e32 v16, v16
	v_rcp_f32_e32 v17, v17
	v_mad_i64_i32 v[20:21], s[0:1], v20, s2, v[138:139]
	v_pk_mul_f32 v[2:3], v[6:7], v[2:3]
	v_pk_mul_f32 v[0:1], v[4:5], v[0:1]
	v_lshl_add_u64 v[20:21], v[20:21], 0, v[140:141]
	v_pk_mul_f32 v[4:5], v[12:13], v[2:3]
	v_pk_mul_f32 v[2:3], v[14:15], v[0:1]
	s_andn2_b64 vcc, exec, s[38:39]
	s_mov_b64 s[0:1], -1
	s_movk_i32 s49, 0x300
	s_mov_b64 s[52:53], 0x60000
	v_pk_mul_f32 v[10:11], v[16:17], v[10:11]
	v_pk_mul_f32 v[8:9], v[18:19], v[8:9]
	s_nop 0
	v_cvt_pk_bf16_f32 v0, v8, v9
	v_cvt_pk_bf16_f32 v1, v10, v11
	v_cvt_pk_bf16_f32 v2, v2, v3
	v_cvt_pk_bf16_f32 v3, v4, v5
	global_store_dwordx4 v[20:21], v[0:3], off nt
	s_cmp_eq_u64 s[8:9], 0
	s_cbranch_scc1 .Lepi_gu2_nb
	s_barrier
; #define PG8_BAR __builtin_amdgcn_s_barrier()
; template <class Epi>
; __device__ __forceinline__ void gemm_phase(LAS unsigned char* lds, const Gemm g, const StaticOrder& S, const Epi& E, const int tid) {
;     ...
;         if (!has_next) break;
;         if (!(Epi::CHAIN && cur.n + 1 < S.NS)) {
; #pragma unroll
;         for (int a = 0; a < 2; ++a)
; #pragma unroll
;             for (int b = 0; b < 2; ++b)
; #pragma unroll
;                 for (int m = 0; m < 4; ++m)
; #pragma unroll
;                     for (int n = 0; n < 2; ++n) acc[a][b][m][n] = (f32x4){0.f, 0.f, 0.f, 0.f};
;         }
;         cur = nxt; cA = nA; cB = nB; ++ui;
;         if (wr == 1) PG8_BAR;
.Lepi_gu2_nb:
	s_cbranch_vccnz .LBB0_1000
	s_andn2_b64 vcc, exec, s[6:7]
	s_cbranch_vccnz .LBB0_999
	s_barrier
	s_branch .LBB0_999
